# BM selected-attention fast path: QK MFMAs tile-major with the scale/bias and exps of finished tiles issued between the MFMAs of later tiles
# speedup vs baseline: 1.0068x; 1.0068x over previous
.Lbm2_nostag:
.Lbm2_blkA:
	s_lshl_b32 s12, s15, 12
	s_add_u32 s30, s46, s12
	s_addc_u32 s31, s47, 0
	global_load_dwordx4 v[20:23], v79, s[30:31]
	global_load_dwordx4 v[24:27], v79, s[30:31] offset:1024
	global_load_dwordx4 v[28:31], v79, s[30:31] offset:2048
	global_load_dwordx4 v[32:35], v79, s[30:31] offset:3072
	s_lshl_b32 s12, s15, 12
	s_add_u32 s30, s62, s12
	s_addc_u32 s31, s63, 0
	global_load_dwordx4 v[52:55], v79, s[30:31]
	global_load_dwordx4 v[56:59], v79, s[30:31] offset:1024
	global_load_dwordx4 v[60:63], v79, s[30:31] offset:2048
	global_load_dwordx4 v[64:67], v79, s[30:31] offset:3072
	s_add_i32 s14, s35, 2
	s_add_i32 s13, s25, -1
	s_min_i32 s14, s14, s13
	s_lshl_b32 s13, s14, 2
	s_add_i32 s13, s13, s96
	v_mov_b32_e32 v76, s13
	ds_read_b32 v76, v76 offset:16384
	s_cmp_ge_i32 s54, s21
	s_cselect_b32 s14, 1, 0
	s_bfe_u32 s29, s48, 0x40000
	s_cmp_eq_u32 s29, 0
	s_cbranch_scc1 .Lbm2_Ag0_skip
	s_waitcnt vmcnt(12)
	v_mfma_f32_16x16x32_fp8_fp8 v[84:87], v[2:3], v[164:165], 0
	v_mfma_f32_16x16x32_fp8_fp8 v[84:87], v[4:5], v[166:167], v[84:87]
	v_mfma_f32_16x16x32_fp8_fp8 v[88:91], v[6:7], v[164:165], 0
	v_mfma_f32_16x16x32_fp8_fp8 v[88:91], v[8:9], v[166:167], v[88:91]
	v_and_b32_e32 v199, s29, v244
	s_cmp_eq_u32 s14, 1
	v_cmp_ne_u32_e32 vcc, 0, v199
	s_cbranch_scc1 .Lbm2_Ag0_near0
	v_add_f32_e32 v200, v81, v190
	v_cndmask_b32_e32 v200, v77, v200, vcc
	s_cmp_eq_u32 s35, 0
	s_cbranch_scc1 .Lbm2_Ag0_first0
	v_mfma_f32_16x16x32_fp8_fp8 v[92:95], v[12:13], v[164:165], 0
	v_mfma_f32_16x16x32_fp8_fp8 v[92:95], v[14:15], v[166:167], v[92:95]
	v_pk_fma_f32 v[84:85], v[84:85], s[16:17], v[200:201] op_sel_hi:[1,1,0]
	v_pk_fma_f32 v[86:87], v[86:87], s[16:17], v[200:201] op_sel_hi:[1,1,0]
	v_mfma_f32_16x16x32_fp8_fp8 v[96:99], v[16:17], v[164:165], 0
	v_mfma_f32_16x16x32_fp8_fp8 v[96:99], v[18:19], v[166:167], v[96:99]
	v_exp_f32_e32 v84, v84
	v_exp_f32_e32 v85, v85
	v_exp_f32_e32 v86, v86
	v_exp_f32_e32 v87, v87
	v_pk_fma_f32 v[88:89], v[88:89], s[16:17], v[200:201] op_sel_hi:[1,1,0]
	v_pk_fma_f32 v[90:91], v[90:91], s[16:17], v[200:201] op_sel_hi:[1,1,0]
	v_exp_f32_e32 v88, v88
	v_exp_f32_e32 v89, v89
	v_exp_f32_e32 v90, v90
	v_exp_f32_e32 v91, v91
	v_pk_fma_f32 v[92:93], v[92:93], s[16:17], v[200:201] op_sel_hi:[1,1,0]
	v_pk_fma_f32 v[94:95], v[94:95], s[16:17], v[200:201] op_sel_hi:[1,1,0]
	v_pk_fma_f32 v[96:97], v[96:97], s[16:17], v[200:201] op_sel_hi:[1,1,0]
	v_pk_fma_f32 v[98:99], v[98:99], s[16:17], v[200:201] op_sel_hi:[1,1,0]
	v_exp_f32_e32 v92, v92
	v_exp_f32_e32 v93, v93
	v_exp_f32_e32 v94, v94
	v_exp_f32_e32 v95, v95
	s_nop 0
	v_exp_f32_e32 v96, v96
	v_exp_f32_e32 v97, v97
	v_exp_f32_e32 v98, v98
	v_exp_f32_e32 v99, v99
	v_pk_add_f32 v[248:249], v[84:85], v[86:87]
	v_pk_add_f32 v[82:83], v[88:89], v[90:91]
	v_pk_add_f32 v[172:173], v[92:93], v[94:95]
	v_pk_add_f32 v[202:203], v[96:97], v[98:99]
	v_cvt_pk_fp8_f32 v84, v84, v85
	v_cvt_pk_fp8_f32 v85, v88, v89
	v_pk_add_f32 v[248:249], v[248:249], v[82:83]
	v_pk_add_f32 v[172:173], v[172:173], v[202:203]
	v_cvt_pk_fp8_f32 v84, v86, v87 op_sel:[0,0,1]
	v_cvt_pk_fp8_f32 v85, v90, v91 op_sel:[0,0,1]
	v_pk_add_f32 v[248:249], v[248:249], v[172:173]
	v_cvt_pk_fp8_f32 v86, v92, v93
	v_cvt_pk_fp8_f32 v87, v96, v97
	v_add_f32_e32 v248, v248, v249
	v_cvt_pk_fp8_f32 v86, v94, v95 op_sel:[0,0,1]
	v_cvt_pk_fp8_f32 v87, v98, v99 op_sel:[0,0,1]
	v_cmp_lt_f32_e32 vcc, 0x43800000, v248
	s_cbranch_vccnz .Lbm2_Ag0_redo
	v_add_f32_e32 v194, v194, v248
	s_waitcnt vmcnt(8)
	v_mfma_f32_16x16x32_fp8_fp8 v[100:103], v[36:37], v[84:85], v[100:103]
	v_mfma_f32_16x16x32_fp8_fp8 v[104:107], v[38:39], v[84:85], v[104:107]
	v_mfma_f32_16x16x32_fp8_fp8 v[108:111], v[40:41], v[84:85], v[108:111]
	v_mfma_f32_16x16x32_fp8_fp8 v[112:115], v[42:43], v[84:85], v[112:115]
	v_mfma_f32_16x16x32_fp8_fp8 v[100:103], v[44:45], v[86:87], v[100:103]
	v_mfma_f32_16x16x32_fp8_fp8 v[104:107], v[46:47], v[86:87], v[104:107]
	v_mfma_f32_16x16x32_fp8_fp8 v[108:111], v[48:49], v[86:87], v[108:111]
	v_mfma_f32_16x16x32_fp8_fp8 v[112:115], v[50:51], v[86:87], v[112:115]
	s_branch .Lbm2_Ag0_skip
.Lbm2_Ag0_first0:
	v_mfma_f32_16x16x32_fp8_fp8 v[92:95], v[12:13], v[164:165], 0
	v_mfma_f32_16x16x32_fp8_fp8 v[92:95], v[14:15], v[166:167], v[92:95]
	v_mfma_f32_16x16x32_fp8_fp8 v[96:99], v[16:17], v[164:165], 0
	v_mfma_f32_16x16x32_fp8_fp8 v[96:99], v[18:19], v[166:167], v[96:99]
	s_nop 7
	s_branch .Lbm2_Ag0_first

.Lbm2_Ag0_near0:
	v_mfma_f32_16x16x32_fp8_fp8 v[92:95], v[12:13], v[164:165], 0
	v_mfma_f32_16x16x32_fp8_fp8 v[92:95], v[14:15], v[166:167], v[92:95]
	v_mfma_f32_16x16x32_fp8_fp8 v[96:99], v[16:17], v[164:165], 0
	v_mfma_f32_16x16x32_fp8_fp8 v[96:99], v[18:19], v[166:167], v[96:99]

.Lbm2_Ag0_skip:
	s_bfe_u32 s29, s48, 0x40004
	s_cmp_eq_u32 s29, 0
	s_cbranch_scc1 .Lbm2_Ag1_skip
	s_waitcnt vmcnt(12)
	v_mfma_f32_16x16x32_fp8_fp8 v[84:87], v[2:3], v[168:169], 0
	v_mfma_f32_16x16x32_fp8_fp8 v[84:87], v[4:5], v[170:171], v[84:87]
	v_mfma_f32_16x16x32_fp8_fp8 v[88:91], v[6:7], v[168:169], 0
	v_mfma_f32_16x16x32_fp8_fp8 v[88:91], v[8:9], v[170:171], v[88:91]
	v_and_b32_e32 v199, s29, v244
	s_cmp_eq_u32 s14, 1
	v_cmp_ne_u32_e32 vcc, 0, v199
	s_cbranch_scc1 .Lbm2_Ag1_near0
	v_add_f32_e32 v200, v81, v191
	v_cndmask_b32_e32 v200, v77, v200, vcc
	s_cmp_eq_u32 s35, 0
	s_cbranch_scc1 .Lbm2_Ag1_first0
	v_mfma_f32_16x16x32_fp8_fp8 v[92:95], v[12:13], v[168:169], 0
	v_mfma_f32_16x16x32_fp8_fp8 v[92:95], v[14:15], v[170:171], v[92:95]
	v_pk_fma_f32 v[84:85], v[84:85], s[16:17], v[200:201] op_sel_hi:[1,1,0]
	v_pk_fma_f32 v[86:87], v[86:87], s[16:17], v[200:201] op_sel_hi:[1,1,0]
	v_mfma_f32_16x16x32_fp8_fp8 v[96:99], v[16:17], v[168:169], 0
	v_mfma_f32_16x16x32_fp8_fp8 v[96:99], v[18:19], v[170:171], v[96:99]
	v_exp_f32_e32 v84, v84
	v_exp_f32_e32 v85, v85
	v_exp_f32_e32 v86, v86
	v_exp_f32_e32 v87, v87
	v_pk_fma_f32 v[88:89], v[88:89], s[16:17], v[200:201] op_sel_hi:[1,1,0]
	v_pk_fma_f32 v[90:91], v[90:91], s[16:17], v[200:201] op_sel_hi:[1,1,0]
	v_exp_f32_e32 v88, v88
	v_exp_f32_e32 v89, v89
	v_exp_f32_e32 v90, v90
	v_exp_f32_e32 v91, v91
	v_pk_fma_f32 v[92:93], v[92:93], s[16:17], v[200:201] op_sel_hi:[1,1,0]
	v_pk_fma_f32 v[94:95], v[94:95], s[16:17], v[200:201] op_sel_hi:[1,1,0]
	v_pk_fma_f32 v[96:97], v[96:97], s[16:17], v[200:201] op_sel_hi:[1,1,0]
	v_pk_fma_f32 v[98:99], v[98:99], s[16:17], v[200:201] op_sel_hi:[1,1,0]
	v_exp_f32_e32 v92, v92
	v_exp_f32_e32 v93, v93
	v_exp_f32_e32 v94, v94
	v_exp_f32_e32 v95, v95
	s_nop 0
	v_exp_f32_e32 v96, v96
	v_exp_f32_e32 v97, v97
	v_exp_f32_e32 v98, v98
	v_exp_f32_e32 v99, v99
	v_pk_add_f32 v[248:249], v[84:85], v[86:87]
	v_pk_add_f32 v[82:83], v[88:89], v[90:91]
	v_pk_add_f32 v[172:173], v[92:93], v[94:95]
	v_pk_add_f32 v[202:203], v[96:97], v[98:99]
	v_cvt_pk_fp8_f32 v84, v84, v85
	v_cvt_pk_fp8_f32 v85, v88, v89
	v_pk_add_f32 v[248:249], v[248:249], v[82:83]
	v_pk_add_f32 v[172:173], v[172:173], v[202:203]
	v_cvt_pk_fp8_f32 v84, v86, v87 op_sel:[0,0,1]
	v_cvt_pk_fp8_f32 v85, v90, v91 op_sel:[0,0,1]
	v_pk_add_f32 v[248:249], v[248:249], v[172:173]
	v_cvt_pk_fp8_f32 v86, v92, v93
	v_cvt_pk_fp8_f32 v87, v96, v97
	v_add_f32_e32 v248, v248, v249
	v_cvt_pk_fp8_f32 v86, v94, v95 op_sel:[0,0,1]
	v_cvt_pk_fp8_f32 v87, v98, v99 op_sel:[0,0,1]
	v_cmp_lt_f32_e32 vcc, 0x43800000, v248
	s_cbranch_vccnz .Lbm2_Ag1_redo
	v_add_f32_e32 v195, v195, v248
	s_waitcnt vmcnt(8)
	v_mfma_f32_16x16x32_fp8_fp8 v[116:119], v[36:37], v[84:85], v[116:119]
	v_mfma_f32_16x16x32_fp8_fp8 v[120:123], v[38:39], v[84:85], v[120:123]
	v_mfma_f32_16x16x32_fp8_fp8 v[124:127], v[40:41], v[84:85], v[124:127]
	v_mfma_f32_16x16x32_fp8_fp8 v[128:131], v[42:43], v[84:85], v[128:131]
	v_mfma_f32_16x16x32_fp8_fp8 v[116:119], v[44:45], v[86:87], v[116:119]
	v_mfma_f32_16x16x32_fp8_fp8 v[120:123], v[46:47], v[86:87], v[120:123]
	v_mfma_f32_16x16x32_fp8_fp8 v[124:127], v[48:49], v[86:87], v[124:127]
	v_mfma_f32_16x16x32_fp8_fp8 v[128:131], v[50:51], v[86:87], v[128:131]
	s_branch .Lbm2_Ag1_skip
.Lbm2_Ag1_first0:
	v_mfma_f32_16x16x32_fp8_fp8 v[92:95], v[12:13], v[168:169], 0
	v_mfma_f32_16x16x32_fp8_fp8 v[92:95], v[14:15], v[170:171], v[92:95]
	v_mfma_f32_16x16x32_fp8_fp8 v[96:99], v[16:17], v[168:169], 0
	v_mfma_f32_16x16x32_fp8_fp8 v[96:99], v[18:19], v[170:171], v[96:99]
	s_nop 7
	s_branch .Lbm2_Ag1_first

.Lbm2_Ag1_near0:
	v_mfma_f32_16x16x32_fp8_fp8 v[92:95], v[12:13], v[168:169], 0
	v_mfma_f32_16x16x32_fp8_fp8 v[92:95], v[14:15], v[170:171], v[92:95]
	v_mfma_f32_16x16x32_fp8_fp8 v[96:99], v[16:17], v[168:169], 0
	v_mfma_f32_16x16x32_fp8_fp8 v[96:99], v[18:19], v[170:171], v[96:99]

.Lbm2_Ag1_skip:
	s_bfe_u32 s29, s48, 0x40008
	s_cmp_eq_u32 s29, 0
	s_cbranch_scc1 .Lbm2_Ag2_skip
	s_waitcnt vmcnt(12)
	v_mfma_f32_16x16x32_fp8_fp8 v[84:87], v[2:3], v[182:183], 0
	v_mfma_f32_16x16x32_fp8_fp8 v[84:87], v[4:5], v[184:185], v[84:87]
	v_mfma_f32_16x16x32_fp8_fp8 v[88:91], v[6:7], v[182:183], 0
	v_mfma_f32_16x16x32_fp8_fp8 v[88:91], v[8:9], v[184:185], v[88:91]
	v_and_b32_e32 v199, s29, v244
	s_cmp_eq_u32 s14, 1
	v_cmp_ne_u32_e32 vcc, 0, v199
	s_cbranch_scc1 .Lbm2_Ag2_near0
	v_add_f32_e32 v200, v81, v192
	v_cndmask_b32_e32 v200, v77, v200, vcc
	s_cmp_eq_u32 s35, 0
	s_cbranch_scc1 .Lbm2_Ag2_first0
	v_mfma_f32_16x16x32_fp8_fp8 v[92:95], v[12:13], v[182:183], 0
	v_mfma_f32_16x16x32_fp8_fp8 v[92:95], v[14:15], v[184:185], v[92:95]
	v_pk_fma_f32 v[84:85], v[84:85], s[16:17], v[200:201] op_sel_hi:[1,1,0]
	v_pk_fma_f32 v[86:87], v[86:87], s[16:17], v[200:201] op_sel_hi:[1,1,0]
	v_mfma_f32_16x16x32_fp8_fp8 v[96:99], v[16:17], v[182:183], 0
	v_mfma_f32_16x16x32_fp8_fp8 v[96:99], v[18:19], v[184:185], v[96:99]
	v_exp_f32_e32 v84, v84
	v_exp_f32_e32 v85, v85
	v_exp_f32_e32 v86, v86
	v_exp_f32_e32 v87, v87
	v_pk_fma_f32 v[88:89], v[88:89], s[16:17], v[200:201] op_sel_hi:[1,1,0]
	v_pk_fma_f32 v[90:91], v[90:91], s[16:17], v[200:201] op_sel_hi:[1,1,0]
	v_exp_f32_e32 v88, v88
	v_exp_f32_e32 v89, v89
	v_exp_f32_e32 v90, v90
	v_exp_f32_e32 v91, v91
	v_pk_fma_f32 v[92:93], v[92:93], s[16:17], v[200:201] op_sel_hi:[1,1,0]
	v_pk_fma_f32 v[94:95], v[94:95], s[16:17], v[200:201] op_sel_hi:[1,1,0]
	v_pk_fma_f32 v[96:97], v[96:97], s[16:17], v[200:201] op_sel_hi:[1,1,0]
	v_pk_fma_f32 v[98:99], v[98:99], s[16:17], v[200:201] op_sel_hi:[1,1,0]
	v_exp_f32_e32 v92, v92
	v_exp_f32_e32 v93, v93
	v_exp_f32_e32 v94, v94
	v_exp_f32_e32 v95, v95
	s_nop 0
	v_exp_f32_e32 v96, v96
	v_exp_f32_e32 v97, v97
	v_exp_f32_e32 v98, v98
	v_exp_f32_e32 v99, v99
	v_pk_add_f32 v[248:249], v[84:85], v[86:87]
	v_pk_add_f32 v[82:83], v[88:89], v[90:91]
	v_pk_add_f32 v[172:173], v[92:93], v[94:95]
	v_pk_add_f32 v[202:203], v[96:97], v[98:99]
	v_cvt_pk_fp8_f32 v84, v84, v85
	v_cvt_pk_fp8_f32 v85, v88, v89
	v_pk_add_f32 v[248:249], v[248:249], v[82:83]
	v_pk_add_f32 v[172:173], v[172:173], v[202:203]
	v_cvt_pk_fp8_f32 v84, v86, v87 op_sel:[0,0,1]
	v_cvt_pk_fp8_f32 v85, v90, v91 op_sel:[0,0,1]
	v_pk_add_f32 v[248:249], v[248:249], v[172:173]
	v_cvt_pk_fp8_f32 v86, v92, v93
	v_cvt_pk_fp8_f32 v87, v96, v97
	v_add_f32_e32 v248, v248, v249
	v_cvt_pk_fp8_f32 v86, v94, v95 op_sel:[0,0,1]
	v_cvt_pk_fp8_f32 v87, v98, v99 op_sel:[0,0,1]
	v_cmp_lt_f32_e32 vcc, 0x43800000, v248
	s_cbranch_vccnz .Lbm2_Ag2_redo
	v_add_f32_e32 v196, v196, v248
	s_waitcnt vmcnt(8)
	v_mfma_f32_16x16x32_fp8_fp8 v[132:135], v[36:37], v[84:85], v[132:135]
	v_mfma_f32_16x16x32_fp8_fp8 v[136:139], v[38:39], v[84:85], v[136:139]
	v_mfma_f32_16x16x32_fp8_fp8 v[140:143], v[40:41], v[84:85], v[140:143]
	v_mfma_f32_16x16x32_fp8_fp8 v[144:147], v[42:43], v[84:85], v[144:147]
	v_mfma_f32_16x16x32_fp8_fp8 v[132:135], v[44:45], v[86:87], v[132:135]
	v_mfma_f32_16x16x32_fp8_fp8 v[136:139], v[46:47], v[86:87], v[136:139]
	v_mfma_f32_16x16x32_fp8_fp8 v[140:143], v[48:49], v[86:87], v[140:143]
	v_mfma_f32_16x16x32_fp8_fp8 v[144:147], v[50:51], v[86:87], v[144:147]
	s_branch .Lbm2_Ag2_skip
.Lbm2_Ag2_first0:
	v_mfma_f32_16x16x32_fp8_fp8 v[92:95], v[12:13], v[182:183], 0
	v_mfma_f32_16x16x32_fp8_fp8 v[92:95], v[14:15], v[184:185], v[92:95]
	v_mfma_f32_16x16x32_fp8_fp8 v[96:99], v[16:17], v[182:183], 0
	v_mfma_f32_16x16x32_fp8_fp8 v[96:99], v[18:19], v[184:185], v[96:99]
	s_nop 7
	s_branch .Lbm2_Ag2_first

.Lbm2_Ag2_near0:
	v_mfma_f32_16x16x32_fp8_fp8 v[92:95], v[12:13], v[182:183], 0
	v_mfma_f32_16x16x32_fp8_fp8 v[92:95], v[14:15], v[184:185], v[92:95]
	v_mfma_f32_16x16x32_fp8_fp8 v[96:99], v[16:17], v[182:183], 0
	v_mfma_f32_16x16x32_fp8_fp8 v[96:99], v[18:19], v[184:185], v[96:99]

.Lbm2_Ag2_skip:
	s_bfe_u32 s29, s48, 0x4000c
	s_cmp_eq_u32 s29, 0
	s_cbranch_scc1 .Lbm2_Ag3_skip
	s_waitcnt vmcnt(12)
	v_mfma_f32_16x16x32_fp8_fp8 v[84:87], v[2:3], v[186:187], 0
	v_mfma_f32_16x16x32_fp8_fp8 v[84:87], v[4:5], v[188:189], v[84:87]
	v_mfma_f32_16x16x32_fp8_fp8 v[88:91], v[6:7], v[186:187], 0
	v_mfma_f32_16x16x32_fp8_fp8 v[88:91], v[8:9], v[188:189], v[88:91]
	v_and_b32_e32 v199, s29, v244
	s_cmp_eq_u32 s14, 1
	v_cmp_ne_u32_e32 vcc, 0, v199
	s_cbranch_scc1 .Lbm2_Ag3_near0
	v_add_f32_e32 v200, v81, v193
	v_cndmask_b32_e32 v200, v77, v200, vcc
	s_cmp_eq_u32 s35, 0
	s_cbranch_scc1 .Lbm2_Ag3_first0
	v_mfma_f32_16x16x32_fp8_fp8 v[92:95], v[12:13], v[186:187], 0
	v_mfma_f32_16x16x32_fp8_fp8 v[92:95], v[14:15], v[188:189], v[92:95]
	v_pk_fma_f32 v[84:85], v[84:85], s[16:17], v[200:201] op_sel_hi:[1,1,0]
	v_pk_fma_f32 v[86:87], v[86:87], s[16:17], v[200:201] op_sel_hi:[1,1,0]
	v_mfma_f32_16x16x32_fp8_fp8 v[96:99], v[16:17], v[186:187], 0
	v_mfma_f32_16x16x32_fp8_fp8 v[96:99], v[18:19], v[188:189], v[96:99]
	v_exp_f32_e32 v84, v84
	v_exp_f32_e32 v85, v85
	v_exp_f32_e32 v86, v86
	v_exp_f32_e32 v87, v87
	v_pk_fma_f32 v[88:89], v[88:89], s[16:17], v[200:201] op_sel_hi:[1,1,0]
	v_pk_fma_f32 v[90:91], v[90:91], s[16:17], v[200:201] op_sel_hi:[1,1,0]
	v_exp_f32_e32 v88, v88
	v_exp_f32_e32 v89, v89
	v_exp_f32_e32 v90, v90
	v_exp_f32_e32 v91, v91
	v_pk_fma_f32 v[92:93], v[92:93], s[16:17], v[200:201] op_sel_hi:[1,1,0]
	v_pk_fma_f32 v[94:95], v[94:95], s[16:17], v[200:201] op_sel_hi:[1,1,0]
	v_pk_fma_f32 v[96:97], v[96:97], s[16:17], v[200:201] op_sel_hi:[1,1,0]
	v_pk_fma_f32 v[98:99], v[98:99], s[16:17], v[200:201] op_sel_hi:[1,1,0]
	v_exp_f32_e32 v92, v92
	v_exp_f32_e32 v93, v93
	v_exp_f32_e32 v94, v94
	v_exp_f32_e32 v95, v95
	s_nop 0
	v_exp_f32_e32 v96, v96
	v_exp_f32_e32 v97, v97
	v_exp_f32_e32 v98, v98
	v_exp_f32_e32 v99, v99
	v_pk_add_f32 v[248:249], v[84:85], v[86:87]
	v_pk_add_f32 v[82:83], v[88:89], v[90:91]
	v_pk_add_f32 v[172:173], v[92:93], v[94:95]
	v_pk_add_f32 v[202:203], v[96:97], v[98:99]
	v_cvt_pk_fp8_f32 v84, v84, v85
	v_cvt_pk_fp8_f32 v85, v88, v89
	v_pk_add_f32 v[248:249], v[248:249], v[82:83]
	v_pk_add_f32 v[172:173], v[172:173], v[202:203]
	v_cvt_pk_fp8_f32 v84, v86, v87 op_sel:[0,0,1]
	v_cvt_pk_fp8_f32 v85, v90, v91 op_sel:[0,0,1]
	v_pk_add_f32 v[248:249], v[248:249], v[172:173]
	v_cvt_pk_fp8_f32 v86, v92, v93
	v_cvt_pk_fp8_f32 v87, v96, v97
	v_add_f32_e32 v248, v248, v249
	v_cvt_pk_fp8_f32 v86, v94, v95 op_sel:[0,0,1]
	v_cvt_pk_fp8_f32 v87, v98, v99 op_sel:[0,0,1]
	v_cmp_lt_f32_e32 vcc, 0x43800000, v248
	s_cbranch_vccnz .Lbm2_Ag3_redo
	v_add_f32_e32 v197, v197, v248
	s_waitcnt vmcnt(8)
	v_mfma_f32_16x16x32_fp8_fp8 v[148:151], v[36:37], v[84:85], v[148:151]
	v_mfma_f32_16x16x32_fp8_fp8 v[152:155], v[38:39], v[84:85], v[152:155]
	v_mfma_f32_16x16x32_fp8_fp8 v[156:159], v[40:41], v[84:85], v[156:159]
	v_mfma_f32_16x16x32_fp8_fp8 v[160:163], v[42:43], v[84:85], v[160:163]
	v_mfma_f32_16x16x32_fp8_fp8 v[148:151], v[44:45], v[86:87], v[148:151]
	v_mfma_f32_16x16x32_fp8_fp8 v[152:155], v[46:47], v[86:87], v[152:155]
	v_mfma_f32_16x16x32_fp8_fp8 v[156:159], v[48:49], v[86:87], v[156:159]
	v_mfma_f32_16x16x32_fp8_fp8 v[160:163], v[50:51], v[86:87], v[160:163]
	s_branch .Lbm2_Ag3_skip
.Lbm2_Ag3_first0:
	v_mfma_f32_16x16x32_fp8_fp8 v[92:95], v[12:13], v[186:187], 0
	v_mfma_f32_16x16x32_fp8_fp8 v[92:95], v[14:15], v[188:189], v[92:95]
	v_mfma_f32_16x16x32_fp8_fp8 v[96:99], v[16:17], v[186:187], 0
	v_mfma_f32_16x16x32_fp8_fp8 v[96:99], v[18:19], v[188:189], v[96:99]
	s_nop 7
	s_branch .Lbm2_Ag3_first

.Lbm2_Ag3_near0:
	v_mfma_f32_16x16x32_fp8_fp8 v[92:95], v[12:13], v[186:187], 0
	v_mfma_f32_16x16x32_fp8_fp8 v[92:95], v[14:15], v[188:189], v[92:95]
	v_mfma_f32_16x16x32_fp8_fp8 v[96:99], v[16:17], v[186:187], 0
	v_mfma_f32_16x16x32_fp8_fp8 v[96:99], v[18:19], v[188:189], v[96:99]

.Lbm2_blkB:
	s_lshl_b32 s12, s15, 12
	s_add_u32 s30, s46, s12
	s_addc_u32 s31, s47, 0
	global_load_dwordx4 v[2:5], v79, s[30:31]
	global_load_dwordx4 v[6:9], v79, s[30:31] offset:1024
	global_load_dwordx4 v[12:15], v79, s[30:31] offset:2048
	global_load_dwordx4 v[16:19], v79, s[30:31] offset:3072
	s_lshl_b32 s12, s15, 12
	s_add_u32 s30, s62, s12
	s_addc_u32 s31, s63, 0
	global_load_dwordx4 v[36:39], v79, s[30:31]
	global_load_dwordx4 v[40:43], v79, s[30:31] offset:1024
	global_load_dwordx4 v[44:47], v79, s[30:31] offset:2048
	global_load_dwordx4 v[48:51], v79, s[30:31] offset:3072
	s_add_i32 s14, s35, 2
	s_add_i32 s13, s25, -1
	s_min_i32 s14, s14, s13
	s_lshl_b32 s13, s14, 2
	s_add_i32 s13, s13, s96
	v_mov_b32_e32 v76, s13
	ds_read_b32 v76, v76 offset:16384
	s_cmp_ge_i32 s54, s21
	s_cselect_b32 s14, 1, 0
	s_bfe_u32 s29, s48, 0x40000
	s_cmp_eq_u32 s29, 0
	s_cbranch_scc1 .Lbm2_Bg0_skip
	s_waitcnt vmcnt(12)
	v_mfma_f32_16x16x32_fp8_fp8 v[84:87], v[20:21], v[164:165], 0
	v_mfma_f32_16x16x32_fp8_fp8 v[84:87], v[22:23], v[166:167], v[84:87]
	v_mfma_f32_16x16x32_fp8_fp8 v[88:91], v[24:25], v[164:165], 0
	v_mfma_f32_16x16x32_fp8_fp8 v[88:91], v[26:27], v[166:167], v[88:91]
	v_and_b32_e32 v199, s29, v244
	s_cmp_eq_u32 s14, 1
	v_cmp_ne_u32_e32 vcc, 0, v199
	s_cbranch_scc1 .Lbm2_Bg0_near0
	v_add_f32_e32 v200, v81, v190
	v_cndmask_b32_e32 v200, v77, v200, vcc
	s_cmp_eq_u32 s35, 0
	s_cbranch_scc1 .Lbm2_Bg0_first0
	v_mfma_f32_16x16x32_fp8_fp8 v[92:95], v[28:29], v[164:165], 0
	v_mfma_f32_16x16x32_fp8_fp8 v[92:95], v[30:31], v[166:167], v[92:95]
	v_pk_fma_f32 v[84:85], v[84:85], s[16:17], v[200:201] op_sel_hi:[1,1,0]
	v_pk_fma_f32 v[86:87], v[86:87], s[16:17], v[200:201] op_sel_hi:[1,1,0]
	v_mfma_f32_16x16x32_fp8_fp8 v[96:99], v[32:33], v[164:165], 0
	v_mfma_f32_16x16x32_fp8_fp8 v[96:99], v[34:35], v[166:167], v[96:99]
	v_exp_f32_e32 v84, v84
	v_exp_f32_e32 v85, v85
	v_exp_f32_e32 v86, v86
	v_exp_f32_e32 v87, v87
	v_pk_fma_f32 v[88:89], v[88:89], s[16:17], v[200:201] op_sel_hi:[1,1,0]
	v_pk_fma_f32 v[90:91], v[90:91], s[16:17], v[200:201] op_sel_hi:[1,1,0]
	v_exp_f32_e32 v88, v88
	v_exp_f32_e32 v89, v89
	v_exp_f32_e32 v90, v90
	v_exp_f32_e32 v91, v91
	v_pk_fma_f32 v[92:93], v[92:93], s[16:17], v[200:201] op_sel_hi:[1,1,0]
	v_pk_fma_f32 v[94:95], v[94:95], s[16:17], v[200:201] op_sel_hi:[1,1,0]
	v_pk_fma_f32 v[96:97], v[96:97], s[16:17], v[200:201] op_sel_hi:[1,1,0]
	v_pk_fma_f32 v[98:99], v[98:99], s[16:17], v[200:201] op_sel_hi:[1,1,0]
	v_exp_f32_e32 v92, v92
	v_exp_f32_e32 v93, v93
	v_exp_f32_e32 v94, v94
	v_exp_f32_e32 v95, v95
	s_nop 0
	v_exp_f32_e32 v96, v96
	v_exp_f32_e32 v97, v97
	v_exp_f32_e32 v98, v98
	v_exp_f32_e32 v99, v99
	v_pk_add_f32 v[248:249], v[84:85], v[86:87]
	v_pk_add_f32 v[82:83], v[88:89], v[90:91]
	v_pk_add_f32 v[172:173], v[92:93], v[94:95]
	v_pk_add_f32 v[202:203], v[96:97], v[98:99]
	v_cvt_pk_fp8_f32 v84, v84, v85
	v_cvt_pk_fp8_f32 v85, v88, v89
	v_pk_add_f32 v[248:249], v[248:249], v[82:83]
	v_pk_add_f32 v[172:173], v[172:173], v[202:203]
	v_cvt_pk_fp8_f32 v84, v86, v87 op_sel:[0,0,1]
	v_cvt_pk_fp8_f32 v85, v90, v91 op_sel:[0,0,1]
	v_pk_add_f32 v[248:249], v[248:249], v[172:173]
	v_cvt_pk_fp8_f32 v86, v92, v93
	v_cvt_pk_fp8_f32 v87, v96, v97
	v_add_f32_e32 v248, v248, v249
	v_cvt_pk_fp8_f32 v86, v94, v95 op_sel:[0,0,1]
	v_cvt_pk_fp8_f32 v87, v98, v99 op_sel:[0,0,1]
	v_cmp_lt_f32_e32 vcc, 0x43800000, v248
	s_cbranch_vccnz .Lbm2_Bg0_redo
	v_add_f32_e32 v194, v194, v248
	s_waitcnt vmcnt(8)
	v_mfma_f32_16x16x32_fp8_fp8 v[100:103], v[52:53], v[84:85], v[100:103]
	v_mfma_f32_16x16x32_fp8_fp8 v[104:107], v[54:55], v[84:85], v[104:107]
	v_mfma_f32_16x16x32_fp8_fp8 v[108:111], v[56:57], v[84:85], v[108:111]
	v_mfma_f32_16x16x32_fp8_fp8 v[112:115], v[58:59], v[84:85], v[112:115]
	v_mfma_f32_16x16x32_fp8_fp8 v[100:103], v[60:61], v[86:87], v[100:103]
	v_mfma_f32_16x16x32_fp8_fp8 v[104:107], v[62:63], v[86:87], v[104:107]
	v_mfma_f32_16x16x32_fp8_fp8 v[108:111], v[64:65], v[86:87], v[108:111]
	v_mfma_f32_16x16x32_fp8_fp8 v[112:115], v[66:67], v[86:87], v[112:115]
	s_branch .Lbm2_Bg0_skip
.Lbm2_Bg0_first0:
	v_mfma_f32_16x16x32_fp8_fp8 v[92:95], v[28:29], v[164:165], 0
	v_mfma_f32_16x16x32_fp8_fp8 v[92:95], v[30:31], v[166:167], v[92:95]
	v_mfma_f32_16x16x32_fp8_fp8 v[96:99], v[32:33], v[164:165], 0
	v_mfma_f32_16x16x32_fp8_fp8 v[96:99], v[34:35], v[166:167], v[96:99]
	s_nop 7
	s_branch .Lbm2_Bg0_first

.Lbm2_Bg0_near0:
	v_mfma_f32_16x16x32_fp8_fp8 v[92:95], v[28:29], v[164:165], 0
	v_mfma_f32_16x16x32_fp8_fp8 v[92:95], v[30:31], v[166:167], v[92:95]
	v_mfma_f32_16x16x32_fp8_fp8 v[96:99], v[32:33], v[164:165], 0
	v_mfma_f32_16x16x32_fp8_fp8 v[96:99], v[34:35], v[166:167], v[96:99]

.Lbm2_Bg0_skip:
	s_bfe_u32 s29, s48, 0x40004
	s_cmp_eq_u32 s29, 0
	s_cbranch_scc1 .Lbm2_Bg1_skip
	s_waitcnt vmcnt(12)
	v_mfma_f32_16x16x32_fp8_fp8 v[84:87], v[20:21], v[168:169], 0
	v_mfma_f32_16x16x32_fp8_fp8 v[84:87], v[22:23], v[170:171], v[84:87]
	v_mfma_f32_16x16x32_fp8_fp8 v[88:91], v[24:25], v[168:169], 0
	v_mfma_f32_16x16x32_fp8_fp8 v[88:91], v[26:27], v[170:171], v[88:91]
	v_and_b32_e32 v199, s29, v244
	s_cmp_eq_u32 s14, 1
	v_cmp_ne_u32_e32 vcc, 0, v199
	s_cbranch_scc1 .Lbm2_Bg1_near0
	v_add_f32_e32 v200, v81, v191
	v_cndmask_b32_e32 v200, v77, v200, vcc
	s_cmp_eq_u32 s35, 0
	s_cbranch_scc1 .Lbm2_Bg1_first0
	v_mfma_f32_16x16x32_fp8_fp8 v[92:95], v[28:29], v[168:169], 0
	v_mfma_f32_16x16x32_fp8_fp8 v[92:95], v[30:31], v[170:171], v[92:95]
	v_pk_fma_f32 v[84:85], v[84:85], s[16:17], v[200:201] op_sel_hi:[1,1,0]
	v_pk_fma_f32 v[86:87], v[86:87], s[16:17], v[200:201] op_sel_hi:[1,1,0]
	v_mfma_f32_16x16x32_fp8_fp8 v[96:99], v[32:33], v[168:169], 0
	v_mfma_f32_16x16x32_fp8_fp8 v[96:99], v[34:35], v[170:171], v[96:99]
	v_exp_f32_e32 v84, v84
	v_exp_f32_e32 v85, v85
	v_exp_f32_e32 v86, v86
	v_exp_f32_e32 v87, v87
	v_pk_fma_f32 v[88:89], v[88:89], s[16:17], v[200:201] op_sel_hi:[1,1,0]
	v_pk_fma_f32 v[90:91], v[90:91], s[16:17], v[200:201] op_sel_hi:[1,1,0]
	v_exp_f32_e32 v88, v88
	v_exp_f32_e32 v89, v89
	v_exp_f32_e32 v90, v90
	v_exp_f32_e32 v91, v91
	v_pk_fma_f32 v[92:93], v[92:93], s[16:17], v[200:201] op_sel_hi:[1,1,0]
	v_pk_fma_f32 v[94:95], v[94:95], s[16:17], v[200:201] op_sel_hi:[1,1,0]
	v_pk_fma_f32 v[96:97], v[96:97], s[16:17], v[200:201] op_sel_hi:[1,1,0]
	v_pk_fma_f32 v[98:99], v[98:99], s[16:17], v[200:201] op_sel_hi:[1,1,0]
	v_exp_f32_e32 v92, v92
	v_exp_f32_e32 v93, v93
	v_exp_f32_e32 v94, v94
	v_exp_f32_e32 v95, v95
	s_nop 0
	v_exp_f32_e32 v96, v96
	v_exp_f32_e32 v97, v97
	v_exp_f32_e32 v98, v98
	v_exp_f32_e32 v99, v99
	v_pk_add_f32 v[248:249], v[84:85], v[86:87]
	v_pk_add_f32 v[82:83], v[88:89], v[90:91]
	v_pk_add_f32 v[172:173], v[92:93], v[94:95]
	v_pk_add_f32 v[202:203], v[96:97], v[98:99]
	v_cvt_pk_fp8_f32 v84, v84, v85
	v_cvt_pk_fp8_f32 v85, v88, v89
	v_pk_add_f32 v[248:249], v[248:249], v[82:83]
	v_pk_add_f32 v[172:173], v[172:173], v[202:203]
	v_cvt_pk_fp8_f32 v84, v86, v87 op_sel:[0,0,1]
	v_cvt_pk_fp8_f32 v85, v90, v91 op_sel:[0,0,1]
	v_pk_add_f32 v[248:249], v[248:249], v[172:173]
	v_cvt_pk_fp8_f32 v86, v92, v93
	v_cvt_pk_fp8_f32 v87, v96, v97
	v_add_f32_e32 v248, v248, v249
	v_cvt_pk_fp8_f32 v86, v94, v95 op_sel:[0,0,1]
	v_cvt_pk_fp8_f32 v87, v98, v99 op_sel:[0,0,1]
	v_cmp_lt_f32_e32 vcc, 0x43800000, v248
	s_cbranch_vccnz .Lbm2_Bg1_redo
	v_add_f32_e32 v195, v195, v248
	s_waitcnt vmcnt(8)
	v_mfma_f32_16x16x32_fp8_fp8 v[116:119], v[52:53], v[84:85], v[116:119]
	v_mfma_f32_16x16x32_fp8_fp8 v[120:123], v[54:55], v[84:85], v[120:123]
	v_mfma_f32_16x16x32_fp8_fp8 v[124:127], v[56:57], v[84:85], v[124:127]
	v_mfma_f32_16x16x32_fp8_fp8 v[128:131], v[58:59], v[84:85], v[128:131]
	v_mfma_f32_16x16x32_fp8_fp8 v[116:119], v[60:61], v[86:87], v[116:119]
	v_mfma_f32_16x16x32_fp8_fp8 v[120:123], v[62:63], v[86:87], v[120:123]
	v_mfma_f32_16x16x32_fp8_fp8 v[124:127], v[64:65], v[86:87], v[124:127]
	v_mfma_f32_16x16x32_fp8_fp8 v[128:131], v[66:67], v[86:87], v[128:131]
	s_branch .Lbm2_Bg1_skip
.Lbm2_Bg1_first0:
	v_mfma_f32_16x16x32_fp8_fp8 v[92:95], v[28:29], v[168:169], 0
	v_mfma_f32_16x16x32_fp8_fp8 v[92:95], v[30:31], v[170:171], v[92:95]
	v_mfma_f32_16x16x32_fp8_fp8 v[96:99], v[32:33], v[168:169], 0
	v_mfma_f32_16x16x32_fp8_fp8 v[96:99], v[34:35], v[170:171], v[96:99]
	s_nop 7
	s_branch .Lbm2_Bg1_first

.Lbm2_Bg1_near0:
	v_mfma_f32_16x16x32_fp8_fp8 v[92:95], v[28:29], v[168:169], 0
	v_mfma_f32_16x16x32_fp8_fp8 v[92:95], v[30:31], v[170:171], v[92:95]
	v_mfma_f32_16x16x32_fp8_fp8 v[96:99], v[32:33], v[168:169], 0
	v_mfma_f32_16x16x32_fp8_fp8 v[96:99], v[34:35], v[170:171], v[96:99]

.Lbm2_Bg1_skip:
	s_bfe_u32 s29, s48, 0x40008
	s_cmp_eq_u32 s29, 0
	s_cbranch_scc1 .Lbm2_Bg2_skip
	s_waitcnt vmcnt(12)
	v_mfma_f32_16x16x32_fp8_fp8 v[84:87], v[20:21], v[182:183], 0
	v_mfma_f32_16x16x32_fp8_fp8 v[84:87], v[22:23], v[184:185], v[84:87]
	v_mfma_f32_16x16x32_fp8_fp8 v[88:91], v[24:25], v[182:183], 0
	v_mfma_f32_16x16x32_fp8_fp8 v[88:91], v[26:27], v[184:185], v[88:91]
	v_and_b32_e32 v199, s29, v244
	s_cmp_eq_u32 s14, 1
	v_cmp_ne_u32_e32 vcc, 0, v199
	s_cbranch_scc1 .Lbm2_Bg2_near0
	v_add_f32_e32 v200, v81, v192
	v_cndmask_b32_e32 v200, v77, v200, vcc
	s_cmp_eq_u32 s35, 0
	s_cbranch_scc1 .Lbm2_Bg2_first0
	v_mfma_f32_16x16x32_fp8_fp8 v[92:95], v[28:29], v[182:183], 0
	v_mfma_f32_16x16x32_fp8_fp8 v[92:95], v[30:31], v[184:185], v[92:95]
	v_pk_fma_f32 v[84:85], v[84:85], s[16:17], v[200:201] op_sel_hi:[1,1,0]
	v_pk_fma_f32 v[86:87], v[86:87], s[16:17], v[200:201] op_sel_hi:[1,1,0]
	v_mfma_f32_16x16x32_fp8_fp8 v[96:99], v[32:33], v[182:183], 0
	v_mfma_f32_16x16x32_fp8_fp8 v[96:99], v[34:35], v[184:185], v[96:99]
	v_exp_f32_e32 v84, v84
	v_exp_f32_e32 v85, v85
	v_exp_f32_e32 v86, v86
	v_exp_f32_e32 v87, v87
	v_pk_fma_f32 v[88:89], v[88:89], s[16:17], v[200:201] op_sel_hi:[1,1,0]
	v_pk_fma_f32 v[90:91], v[90:91], s[16:17], v[200:201] op_sel_hi:[1,1,0]
	v_exp_f32_e32 v88, v88
	v_exp_f32_e32 v89, v89
	v_exp_f32_e32 v90, v90
	v_exp_f32_e32 v91, v91
	v_pk_fma_f32 v[92:93], v[92:93], s[16:17], v[200:201] op_sel_hi:[1,1,0]
	v_pk_fma_f32 v[94:95], v[94:95], s[16:17], v[200:201] op_sel_hi:[1,1,0]
	v_pk_fma_f32 v[96:97], v[96:97], s[16:17], v[200:201] op_sel_hi:[1,1,0]
	v_pk_fma_f32 v[98:99], v[98:99], s[16:17], v[200:201] op_sel_hi:[1,1,0]
	v_exp_f32_e32 v92, v92
	v_exp_f32_e32 v93, v93
	v_exp_f32_e32 v94, v94
	v_exp_f32_e32 v95, v95
	s_nop 0
	v_exp_f32_e32 v96, v96
	v_exp_f32_e32 v97, v97
	v_exp_f32_e32 v98, v98
	v_exp_f32_e32 v99, v99
	v_pk_add_f32 v[248:249], v[84:85], v[86:87]
	v_pk_add_f32 v[82:83], v[88:89], v[90:91]
	v_pk_add_f32 v[172:173], v[92:93], v[94:95]
	v_pk_add_f32 v[202:203], v[96:97], v[98:99]
	v_cvt_pk_fp8_f32 v84, v84, v85
	v_cvt_pk_fp8_f32 v85, v88, v89
	v_pk_add_f32 v[248:249], v[248:249], v[82:83]
	v_pk_add_f32 v[172:173], v[172:173], v[202:203]
	v_cvt_pk_fp8_f32 v84, v86, v87 op_sel:[0,0,1]
	v_cvt_pk_fp8_f32 v85, v90, v91 op_sel:[0,0,1]
	v_pk_add_f32 v[248:249], v[248:249], v[172:173]
	v_cvt_pk_fp8_f32 v86, v92, v93
	v_cvt_pk_fp8_f32 v87, v96, v97
	v_add_f32_e32 v248, v248, v249
	v_cvt_pk_fp8_f32 v86, v94, v95 op_sel:[0,0,1]
	v_cvt_pk_fp8_f32 v87, v98, v99 op_sel:[0,0,1]
	v_cmp_lt_f32_e32 vcc, 0x43800000, v248
	s_cbranch_vccnz .Lbm2_Bg2_redo
	v_add_f32_e32 v196, v196, v248
	s_waitcnt vmcnt(8)
	v_mfma_f32_16x16x32_fp8_fp8 v[132:135], v[52:53], v[84:85], v[132:135]
	v_mfma_f32_16x16x32_fp8_fp8 v[136:139], v[54:55], v[84:85], v[136:139]
	v_mfma_f32_16x16x32_fp8_fp8 v[140:143], v[56:57], v[84:85], v[140:143]
	v_mfma_f32_16x16x32_fp8_fp8 v[144:147], v[58:59], v[84:85], v[144:147]
	v_mfma_f32_16x16x32_fp8_fp8 v[132:135], v[60:61], v[86:87], v[132:135]
	v_mfma_f32_16x16x32_fp8_fp8 v[136:139], v[62:63], v[86:87], v[136:139]
	v_mfma_f32_16x16x32_fp8_fp8 v[140:143], v[64:65], v[86:87], v[140:143]
	v_mfma_f32_16x16x32_fp8_fp8 v[144:147], v[66:67], v[86:87], v[144:147]
	s_branch .Lbm2_Bg2_skip
.Lbm2_Bg2_first0:
	v_mfma_f32_16x16x32_fp8_fp8 v[92:95], v[28:29], v[182:183], 0
	v_mfma_f32_16x16x32_fp8_fp8 v[92:95], v[30:31], v[184:185], v[92:95]
	v_mfma_f32_16x16x32_fp8_fp8 v[96:99], v[32:33], v[182:183], 0
	v_mfma_f32_16x16x32_fp8_fp8 v[96:99], v[34:35], v[184:185], v[96:99]
	s_nop 7
	s_branch .Lbm2_Bg2_first

.Lbm2_Bg2_near0:
	v_mfma_f32_16x16x32_fp8_fp8 v[92:95], v[28:29], v[182:183], 0
	v_mfma_f32_16x16x32_fp8_fp8 v[92:95], v[30:31], v[184:185], v[92:95]
	v_mfma_f32_16x16x32_fp8_fp8 v[96:99], v[32:33], v[182:183], 0
	v_mfma_f32_16x16x32_fp8_fp8 v[96:99], v[34:35], v[184:185], v[96:99]

.Lbm2_Bg2_skip:
	s_bfe_u32 s29, s48, 0x4000c
	s_cmp_eq_u32 s29, 0
	s_cbranch_scc1 .Lbm2_Bg3_skip
	s_waitcnt vmcnt(12)
	v_mfma_f32_16x16x32_fp8_fp8 v[84:87], v[20:21], v[186:187], 0
	v_mfma_f32_16x16x32_fp8_fp8 v[84:87], v[22:23], v[188:189], v[84:87]
	v_mfma_f32_16x16x32_fp8_fp8 v[88:91], v[24:25], v[186:187], 0
	v_mfma_f32_16x16x32_fp8_fp8 v[88:91], v[26:27], v[188:189], v[88:91]
	v_and_b32_e32 v199, s29, v244
	s_cmp_eq_u32 s14, 1
	v_cmp_ne_u32_e32 vcc, 0, v199
	s_cbranch_scc1 .Lbm2_Bg3_near0
	v_add_f32_e32 v200, v81, v193
	v_cndmask_b32_e32 v200, v77, v200, vcc
	s_cmp_eq_u32 s35, 0
	s_cbranch_scc1 .Lbm2_Bg3_first0
	v_mfma_f32_16x16x32_fp8_fp8 v[92:95], v[28:29], v[186:187], 0
	v_mfma_f32_16x16x32_fp8_fp8 v[92:95], v[30:31], v[188:189], v[92:95]
	v_pk_fma_f32 v[84:85], v[84:85], s[16:17], v[200:201] op_sel_hi:[1,1,0]
	v_pk_fma_f32 v[86:87], v[86:87], s[16:17], v[200:201] op_sel_hi:[1,1,0]
	v_mfma_f32_16x16x32_fp8_fp8 v[96:99], v[32:33], v[186:187], 0
	v_mfma_f32_16x16x32_fp8_fp8 v[96:99], v[34:35], v[188:189], v[96:99]
	v_exp_f32_e32 v84, v84
	v_exp_f32_e32 v85, v85
	v_exp_f32_e32 v86, v86
	v_exp_f32_e32 v87, v87
	v_pk_fma_f32 v[88:89], v[88:89], s[16:17], v[200:201] op_sel_hi:[1,1,0]
	v_pk_fma_f32 v[90:91], v[90:91], s[16:17], v[200:201] op_sel_hi:[1,1,0]
	v_exp_f32_e32 v88, v88
	v_exp_f32_e32 v89, v89
	v_exp_f32_e32 v90, v90
	v_exp_f32_e32 v91, v91
	v_pk_fma_f32 v[92:93], v[92:93], s[16:17], v[200:201] op_sel_hi:[1,1,0]
	v_pk_fma_f32 v[94:95], v[94:95], s[16:17], v[200:201] op_sel_hi:[1,1,0]
	v_pk_fma_f32 v[96:97], v[96:97], s[16:17], v[200:201] op_sel_hi:[1,1,0]
	v_pk_fma_f32 v[98:99], v[98:99], s[16:17], v[200:201] op_sel_hi:[1,1,0]
	v_exp_f32_e32 v92, v92
	v_exp_f32_e32 v93, v93
	v_exp_f32_e32 v94, v94
	v_exp_f32_e32 v95, v95
	s_nop 0
	v_exp_f32_e32 v96, v96
	v_exp_f32_e32 v97, v97
	v_exp_f32_e32 v98, v98
	v_exp_f32_e32 v99, v99
	v_pk_add_f32 v[248:249], v[84:85], v[86:87]
	v_pk_add_f32 v[82:83], v[88:89], v[90:91]
	v_pk_add_f32 v[172:173], v[92:93], v[94:95]
	v_pk_add_f32 v[202:203], v[96:97], v[98:99]
	v_cvt_pk_fp8_f32 v84, v84, v85
	v_cvt_pk_fp8_f32 v85, v88, v89
	v_pk_add_f32 v[248:249], v[248:249], v[82:83]
	v_pk_add_f32 v[172:173], v[172:173], v[202:203]
	v_cvt_pk_fp8_f32 v84, v86, v87 op_sel:[0,0,1]
	v_cvt_pk_fp8_f32 v85, v90, v91 op_sel:[0,0,1]
	v_pk_add_f32 v[248:249], v[248:249], v[172:173]
	v_cvt_pk_fp8_f32 v86, v92, v93
	v_cvt_pk_fp8_f32 v87, v96, v97
	v_add_f32_e32 v248, v248, v249
	v_cvt_pk_fp8_f32 v86, v94, v95 op_sel:[0,0,1]
	v_cvt_pk_fp8_f32 v87, v98, v99 op_sel:[0,0,1]
	v_cmp_lt_f32_e32 vcc, 0x43800000, v248
	s_cbranch_vccnz .Lbm2_Bg3_redo
	v_add_f32_e32 v197, v197, v248
	s_waitcnt vmcnt(8)
	v_mfma_f32_16x16x32_fp8_fp8 v[148:151], v[52:53], v[84:85], v[148:151]
	v_mfma_f32_16x16x32_fp8_fp8 v[152:155], v[54:55], v[84:85], v[152:155]
	v_mfma_f32_16x16x32_fp8_fp8 v[156:159], v[56:57], v[84:85], v[156:159]
	v_mfma_f32_16x16x32_fp8_fp8 v[160:163], v[58:59], v[84:85], v[160:163]
	v_mfma_f32_16x16x32_fp8_fp8 v[148:151], v[60:61], v[86:87], v[148:151]
	v_mfma_f32_16x16x32_fp8_fp8 v[152:155], v[62:63], v[86:87], v[152:155]
	v_mfma_f32_16x16x32_fp8_fp8 v[156:159], v[64:65], v[86:87], v[156:159]
	v_mfma_f32_16x16x32_fp8_fp8 v[160:163], v[66:67], v[86:87], v[160:163]
	s_branch .Lbm2_Bg3_skip
.Lbm2_Bg3_first0:
	v_mfma_f32_16x16x32_fp8_fp8 v[92:95], v[28:29], v[186:187], 0
	v_mfma_f32_16x16x32_fp8_fp8 v[92:95], v[30:31], v[188:189], v[92:95]
	v_mfma_f32_16x16x32_fp8_fp8 v[96:99], v[32:33], v[186:187], 0
	v_mfma_f32_16x16x32_fp8_fp8 v[96:99], v[34:35], v[188:189], v[96:99]
	s_nop 7
	s_branch .Lbm2_Bg3_first

.Lbm2_Bg3_near0:
	v_mfma_f32_16x16x32_fp8_fp8 v[92:95], v[28:29], v[186:187], 0
	v_mfma_f32_16x16x32_fp8_fp8 v[92:95], v[30:31], v[188:189], v[92:95]
	v_mfma_f32_16x16x32_fp8_fp8 v[96:99], v[32:33], v[186:187], 0
	v_mfma_f32_16x16x32_fp8_fp8 v[96:99], v[34:35], v[188:189], v[96:99]

.Lbm3_nostag:
.Lbm3_blkA:
	s_lshl_b32 s29, s27, 12
	s_add_u32 s30, s40, s29
	s_addc_u32 s31, s41, 0
	global_load_dwordx4 v[20:23], v79, s[30:31]
	global_load_dwordx4 v[24:27], v79, s[30:31] offset:1024
	global_load_dwordx4 v[28:31], v79, s[30:31] offset:2048
	global_load_dwordx4 v[32:35], v79, s[30:31] offset:3072
	s_lshl_b32 s29, s27, 12
	s_add_u32 s30, s62, s29
	s_addc_u32 s31, s63, 0
	global_load_dwordx4 v[52:55], v79, s[30:31]
	global_load_dwordx4 v[56:59], v79, s[30:31] offset:1024
	global_load_dwordx4 v[60:63], v79, s[30:31] offset:2048
	global_load_dwordx4 v[64:67], v79, s[30:31] offset:3072
	s_add_i32 s50, s35, 2
	s_add_i32 s9, s25, -1
	s_min_i32 s50, s50, s9
	s_lshl_b32 s9, s50, 2
	s_add_i32 s9, s9, s46
	v_mov_b32_e32 v76, s9
	ds_read_b32 v76, v76 offset:16384
	s_cmp_ge_i32 s38, s21
	s_cselect_b32 s50, 1, 0
	s_bfe_u32 s29, s48, 0x40000
	s_cmp_eq_u32 s29, 0
	s_cbranch_scc1 .Lbm3_Ag0_skip
	s_waitcnt vmcnt(12)
	v_mfma_f32_16x16x32_fp8_fp8 v[84:87], v[2:3], v[164:165], 0
	v_mfma_f32_16x16x32_fp8_fp8 v[84:87], v[4:5], v[166:167], v[84:87]
	v_mfma_f32_16x16x32_fp8_fp8 v[88:91], v[6:7], v[164:165], 0
	v_mfma_f32_16x16x32_fp8_fp8 v[88:91], v[8:9], v[166:167], v[88:91]
	v_and_b32_e32 v199, s29, v244
	s_cmp_eq_u32 s50, 1
	v_cmp_ne_u32_e32 vcc, 0, v199
	s_cbranch_scc1 .Lbm3_Ag0_near0
	v_add_f32_e32 v200, v81, v190
	v_cndmask_b32_e32 v200, v77, v200, vcc
	s_cmp_eq_u32 s35, 0
	s_cbranch_scc1 .Lbm3_Ag0_first0
	v_mfma_f32_16x16x32_fp8_fp8 v[92:95], v[12:13], v[164:165], 0
	v_mfma_f32_16x16x32_fp8_fp8 v[92:95], v[14:15], v[166:167], v[92:95]
	v_pk_fma_f32 v[84:85], v[84:85], s[10:11], v[200:201] op_sel_hi:[1,1,0]
	v_pk_fma_f32 v[86:87], v[86:87], s[10:11], v[200:201] op_sel_hi:[1,1,0]
	v_mfma_f32_16x16x32_fp8_fp8 v[96:99], v[16:17], v[164:165], 0
	v_mfma_f32_16x16x32_fp8_fp8 v[96:99], v[18:19], v[166:167], v[96:99]
	v_exp_f32_e32 v84, v84
	v_exp_f32_e32 v85, v85
	v_exp_f32_e32 v86, v86
	v_exp_f32_e32 v87, v87
	v_pk_fma_f32 v[88:89], v[88:89], s[10:11], v[200:201] op_sel_hi:[1,1,0]
	v_pk_fma_f32 v[90:91], v[90:91], s[10:11], v[200:201] op_sel_hi:[1,1,0]
	v_exp_f32_e32 v88, v88
	v_exp_f32_e32 v89, v89
	v_exp_f32_e32 v90, v90
	v_exp_f32_e32 v91, v91
	v_pk_fma_f32 v[92:93], v[92:93], s[10:11], v[200:201] op_sel_hi:[1,1,0]
	v_pk_fma_f32 v[94:95], v[94:95], s[10:11], v[200:201] op_sel_hi:[1,1,0]
	v_pk_fma_f32 v[96:97], v[96:97], s[10:11], v[200:201] op_sel_hi:[1,1,0]
	v_pk_fma_f32 v[98:99], v[98:99], s[10:11], v[200:201] op_sel_hi:[1,1,0]
	v_exp_f32_e32 v92, v92
	v_exp_f32_e32 v93, v93
	v_exp_f32_e32 v94, v94
	v_exp_f32_e32 v95, v95
	s_nop 0
	v_exp_f32_e32 v96, v96
	v_exp_f32_e32 v97, v97
	v_exp_f32_e32 v98, v98
	v_exp_f32_e32 v99, v99
	v_pk_add_f32 v[248:249], v[84:85], v[86:87]
	v_pk_add_f32 v[82:83], v[88:89], v[90:91]
	v_pk_add_f32 v[172:173], v[92:93], v[94:95]
	v_pk_add_f32 v[202:203], v[96:97], v[98:99]
	v_cvt_pk_fp8_f32 v84, v84, v85
	v_cvt_pk_fp8_f32 v85, v88, v89
	v_pk_add_f32 v[248:249], v[248:249], v[82:83]
	v_pk_add_f32 v[172:173], v[172:173], v[202:203]
	v_cvt_pk_fp8_f32 v84, v86, v87 op_sel:[0,0,1]
	v_cvt_pk_fp8_f32 v85, v90, v91 op_sel:[0,0,1]
	v_pk_add_f32 v[248:249], v[248:249], v[172:173]
	v_cvt_pk_fp8_f32 v86, v92, v93
	v_cvt_pk_fp8_f32 v87, v96, v97
	v_add_f32_e32 v248, v248, v249
	v_cvt_pk_fp8_f32 v86, v94, v95 op_sel:[0,0,1]
	v_cvt_pk_fp8_f32 v87, v98, v99 op_sel:[0,0,1]
	v_cmp_lt_f32_e32 vcc, 0x43800000, v248
	s_cbranch_vccnz .Lbm3_Ag0_redo
	v_add_f32_e32 v194, v194, v248
	s_waitcnt vmcnt(8)
	v_mfma_f32_16x16x32_fp8_fp8 v[100:103], v[36:37], v[84:85], v[100:103]
	v_mfma_f32_16x16x32_fp8_fp8 v[104:107], v[38:39], v[84:85], v[104:107]
	v_mfma_f32_16x16x32_fp8_fp8 v[108:111], v[40:41], v[84:85], v[108:111]
	v_mfma_f32_16x16x32_fp8_fp8 v[112:115], v[42:43], v[84:85], v[112:115]
	v_mfma_f32_16x16x32_fp8_fp8 v[100:103], v[44:45], v[86:87], v[100:103]
	v_mfma_f32_16x16x32_fp8_fp8 v[104:107], v[46:47], v[86:87], v[104:107]
	v_mfma_f32_16x16x32_fp8_fp8 v[108:111], v[48:49], v[86:87], v[108:111]
	v_mfma_f32_16x16x32_fp8_fp8 v[112:115], v[50:51], v[86:87], v[112:115]
	s_branch .Lbm3_Ag0_skip

.Lbm3_Ag0_skip:
	s_bfe_u32 s29, s48, 0x40004
	s_cmp_eq_u32 s29, 0
	s_cbranch_scc1 .Lbm3_Ag1_skip
	s_waitcnt vmcnt(12)
	v_mfma_f32_16x16x32_fp8_fp8 v[84:87], v[2:3], v[168:169], 0
	v_mfma_f32_16x16x32_fp8_fp8 v[84:87], v[4:5], v[170:171], v[84:87]
	v_mfma_f32_16x16x32_fp8_fp8 v[88:91], v[6:7], v[168:169], 0
	v_mfma_f32_16x16x32_fp8_fp8 v[88:91], v[8:9], v[170:171], v[88:91]
	v_and_b32_e32 v199, s29, v244
	s_cmp_eq_u32 s50, 1
	v_cmp_ne_u32_e32 vcc, 0, v199
	s_cbranch_scc1 .Lbm3_Ag1_near0
	v_add_f32_e32 v200, v81, v191
	v_cndmask_b32_e32 v200, v77, v200, vcc
	s_cmp_eq_u32 s35, 0
	s_cbranch_scc1 .Lbm3_Ag1_first0
	v_mfma_f32_16x16x32_fp8_fp8 v[92:95], v[12:13], v[168:169], 0
	v_mfma_f32_16x16x32_fp8_fp8 v[92:95], v[14:15], v[170:171], v[92:95]
	v_pk_fma_f32 v[84:85], v[84:85], s[10:11], v[200:201] op_sel_hi:[1,1,0]
	v_pk_fma_f32 v[86:87], v[86:87], s[10:11], v[200:201] op_sel_hi:[1,1,0]
	v_mfma_f32_16x16x32_fp8_fp8 v[96:99], v[16:17], v[168:169], 0
	v_mfma_f32_16x16x32_fp8_fp8 v[96:99], v[18:19], v[170:171], v[96:99]
	v_exp_f32_e32 v84, v84
	v_exp_f32_e32 v85, v85
	v_exp_f32_e32 v86, v86
	v_exp_f32_e32 v87, v87
	v_pk_fma_f32 v[88:89], v[88:89], s[10:11], v[200:201] op_sel_hi:[1,1,0]
	v_pk_fma_f32 v[90:91], v[90:91], s[10:11], v[200:201] op_sel_hi:[1,1,0]
	v_exp_f32_e32 v88, v88
	v_exp_f32_e32 v89, v89
	v_exp_f32_e32 v90, v90
	v_exp_f32_e32 v91, v91
	v_pk_fma_f32 v[92:93], v[92:93], s[10:11], v[200:201] op_sel_hi:[1,1,0]
	v_pk_fma_f32 v[94:95], v[94:95], s[10:11], v[200:201] op_sel_hi:[1,1,0]
	v_pk_fma_f32 v[96:97], v[96:97], s[10:11], v[200:201] op_sel_hi:[1,1,0]
	v_pk_fma_f32 v[98:99], v[98:99], s[10:11], v[200:201] op_sel_hi:[1,1,0]
	v_exp_f32_e32 v92, v92
	v_exp_f32_e32 v93, v93
	v_exp_f32_e32 v94, v94
	v_exp_f32_e32 v95, v95
	s_nop 0
	v_exp_f32_e32 v96, v96
	v_exp_f32_e32 v97, v97
	v_exp_f32_e32 v98, v98
	v_exp_f32_e32 v99, v99
	v_pk_add_f32 v[248:249], v[84:85], v[86:87]
	v_pk_add_f32 v[82:83], v[88:89], v[90:91]
	v_pk_add_f32 v[172:173], v[92:93], v[94:95]
	v_pk_add_f32 v[202:203], v[96:97], v[98:99]
	v_cvt_pk_fp8_f32 v84, v84, v85
	v_cvt_pk_fp8_f32 v85, v88, v89
	v_pk_add_f32 v[248:249], v[248:249], v[82:83]
	v_pk_add_f32 v[172:173], v[172:173], v[202:203]
	v_cvt_pk_fp8_f32 v84, v86, v87 op_sel:[0,0,1]
	v_cvt_pk_fp8_f32 v85, v90, v91 op_sel:[0,0,1]
	v_pk_add_f32 v[248:249], v[248:249], v[172:173]
	v_cvt_pk_fp8_f32 v86, v92, v93
	v_cvt_pk_fp8_f32 v87, v96, v97
	v_add_f32_e32 v248, v248, v249
	v_cvt_pk_fp8_f32 v86, v94, v95 op_sel:[0,0,1]
	v_cvt_pk_fp8_f32 v87, v98, v99 op_sel:[0,0,1]
	v_cmp_lt_f32_e32 vcc, 0x43800000, v248
	s_cbranch_vccnz .Lbm3_Ag1_redo
	v_add_f32_e32 v195, v195, v248
	s_waitcnt vmcnt(8)
	v_mfma_f32_16x16x32_fp8_fp8 v[116:119], v[36:37], v[84:85], v[116:119]
	v_mfma_f32_16x16x32_fp8_fp8 v[120:123], v[38:39], v[84:85], v[120:123]
	v_mfma_f32_16x16x32_fp8_fp8 v[124:127], v[40:41], v[84:85], v[124:127]
	v_mfma_f32_16x16x32_fp8_fp8 v[128:131], v[42:43], v[84:85], v[128:131]
	v_mfma_f32_16x16x32_fp8_fp8 v[116:119], v[44:45], v[86:87], v[116:119]
	v_mfma_f32_16x16x32_fp8_fp8 v[120:123], v[46:47], v[86:87], v[120:123]
	v_mfma_f32_16x16x32_fp8_fp8 v[124:127], v[48:49], v[86:87], v[124:127]
	v_mfma_f32_16x16x32_fp8_fp8 v[128:131], v[50:51], v[86:87], v[128:131]
	s_branch .Lbm3_Ag1_skip

.Lbm3_Ag1_skip:
	s_bfe_u32 s29, s48, 0x40008
	s_cmp_eq_u32 s29, 0
	s_cbranch_scc1 .Lbm3_Ag2_skip
	s_waitcnt vmcnt(12)
	v_mfma_f32_16x16x32_fp8_fp8 v[84:87], v[2:3], v[182:183], 0
	v_mfma_f32_16x16x32_fp8_fp8 v[84:87], v[4:5], v[184:185], v[84:87]
	v_mfma_f32_16x16x32_fp8_fp8 v[88:91], v[6:7], v[182:183], 0
	v_mfma_f32_16x16x32_fp8_fp8 v[88:91], v[8:9], v[184:185], v[88:91]
	v_and_b32_e32 v199, s29, v244
	s_cmp_eq_u32 s50, 1
	v_cmp_ne_u32_e32 vcc, 0, v199
	s_cbranch_scc1 .Lbm3_Ag2_near0
	v_add_f32_e32 v200, v81, v192
	v_cndmask_b32_e32 v200, v77, v200, vcc
	s_cmp_eq_u32 s35, 0
	s_cbranch_scc1 .Lbm3_Ag2_first0
	v_mfma_f32_16x16x32_fp8_fp8 v[92:95], v[12:13], v[182:183], 0
	v_mfma_f32_16x16x32_fp8_fp8 v[92:95], v[14:15], v[184:185], v[92:95]
	v_pk_fma_f32 v[84:85], v[84:85], s[10:11], v[200:201] op_sel_hi:[1,1,0]
	v_pk_fma_f32 v[86:87], v[86:87], s[10:11], v[200:201] op_sel_hi:[1,1,0]
	v_mfma_f32_16x16x32_fp8_fp8 v[96:99], v[16:17], v[182:183], 0
	v_mfma_f32_16x16x32_fp8_fp8 v[96:99], v[18:19], v[184:185], v[96:99]
	v_exp_f32_e32 v84, v84
	v_exp_f32_e32 v85, v85
	v_exp_f32_e32 v86, v86
	v_exp_f32_e32 v87, v87
	v_pk_fma_f32 v[88:89], v[88:89], s[10:11], v[200:201] op_sel_hi:[1,1,0]
	v_pk_fma_f32 v[90:91], v[90:91], s[10:11], v[200:201] op_sel_hi:[1,1,0]
	v_exp_f32_e32 v88, v88
	v_exp_f32_e32 v89, v89
	v_exp_f32_e32 v90, v90
	v_exp_f32_e32 v91, v91
	v_pk_fma_f32 v[92:93], v[92:93], s[10:11], v[200:201] op_sel_hi:[1,1,0]
	v_pk_fma_f32 v[94:95], v[94:95], s[10:11], v[200:201] op_sel_hi:[1,1,0]
	v_pk_fma_f32 v[96:97], v[96:97], s[10:11], v[200:201] op_sel_hi:[1,1,0]
	v_pk_fma_f32 v[98:99], v[98:99], s[10:11], v[200:201] op_sel_hi:[1,1,0]
	v_exp_f32_e32 v92, v92
	v_exp_f32_e32 v93, v93
	v_exp_f32_e32 v94, v94
	v_exp_f32_e32 v95, v95
	s_nop 0
	v_exp_f32_e32 v96, v96
	v_exp_f32_e32 v97, v97
	v_exp_f32_e32 v98, v98
	v_exp_f32_e32 v99, v99
	v_pk_add_f32 v[248:249], v[84:85], v[86:87]
	v_pk_add_f32 v[82:83], v[88:89], v[90:91]
	v_pk_add_f32 v[172:173], v[92:93], v[94:95]
	v_pk_add_f32 v[202:203], v[96:97], v[98:99]
	v_cvt_pk_fp8_f32 v84, v84, v85
	v_cvt_pk_fp8_f32 v85, v88, v89
	v_pk_add_f32 v[248:249], v[248:249], v[82:83]
	v_pk_add_f32 v[172:173], v[172:173], v[202:203]
	v_cvt_pk_fp8_f32 v84, v86, v87 op_sel:[0,0,1]
	v_cvt_pk_fp8_f32 v85, v90, v91 op_sel:[0,0,1]
	v_pk_add_f32 v[248:249], v[248:249], v[172:173]
	v_cvt_pk_fp8_f32 v86, v92, v93
	v_cvt_pk_fp8_f32 v87, v96, v97
	v_add_f32_e32 v248, v248, v249
	v_cvt_pk_fp8_f32 v86, v94, v95 op_sel:[0,0,1]
	v_cvt_pk_fp8_f32 v87, v98, v99 op_sel:[0,0,1]
	v_cmp_lt_f32_e32 vcc, 0x43800000, v248
	s_cbranch_vccnz .Lbm3_Ag2_redo
	v_add_f32_e32 v196, v196, v248
	s_waitcnt vmcnt(8)
	v_mfma_f32_16x16x32_fp8_fp8 v[132:135], v[36:37], v[84:85], v[132:135]
	v_mfma_f32_16x16x32_fp8_fp8 v[136:139], v[38:39], v[84:85], v[136:139]
	v_mfma_f32_16x16x32_fp8_fp8 v[140:143], v[40:41], v[84:85], v[140:143]
	v_mfma_f32_16x16x32_fp8_fp8 v[144:147], v[42:43], v[84:85], v[144:147]
	v_mfma_f32_16x16x32_fp8_fp8 v[132:135], v[44:45], v[86:87], v[132:135]
	v_mfma_f32_16x16x32_fp8_fp8 v[136:139], v[46:47], v[86:87], v[136:139]
	v_mfma_f32_16x16x32_fp8_fp8 v[140:143], v[48:49], v[86:87], v[140:143]
	v_mfma_f32_16x16x32_fp8_fp8 v[144:147], v[50:51], v[86:87], v[144:147]
	s_branch .Lbm3_Ag2_skip

.Lbm3_Ag2_skip:
	s_bfe_u32 s29, s48, 0x4000c
	s_cmp_eq_u32 s29, 0
	s_cbranch_scc1 .Lbm3_Ag3_skip
	s_waitcnt vmcnt(12)
	v_mfma_f32_16x16x32_fp8_fp8 v[84:87], v[2:3], v[186:187], 0
	v_mfma_f32_16x16x32_fp8_fp8 v[84:87], v[4:5], v[188:189], v[84:87]
	v_mfma_f32_16x16x32_fp8_fp8 v[88:91], v[6:7], v[186:187], 0
	v_mfma_f32_16x16x32_fp8_fp8 v[88:91], v[8:9], v[188:189], v[88:91]
	v_and_b32_e32 v199, s29, v244
	s_cmp_eq_u32 s50, 1
	v_cmp_ne_u32_e32 vcc, 0, v199
	s_cbranch_scc1 .Lbm3_Ag3_near0
	v_add_f32_e32 v200, v81, v193
	v_cndmask_b32_e32 v200, v77, v200, vcc
	s_cmp_eq_u32 s35, 0
	s_cbranch_scc1 .Lbm3_Ag3_first0
	v_mfma_f32_16x16x32_fp8_fp8 v[92:95], v[12:13], v[186:187], 0
	v_mfma_f32_16x16x32_fp8_fp8 v[92:95], v[14:15], v[188:189], v[92:95]
	v_pk_fma_f32 v[84:85], v[84:85], s[10:11], v[200:201] op_sel_hi:[1,1,0]
	v_pk_fma_f32 v[86:87], v[86:87], s[10:11], v[200:201] op_sel_hi:[1,1,0]
	v_mfma_f32_16x16x32_fp8_fp8 v[96:99], v[16:17], v[186:187], 0
	v_mfma_f32_16x16x32_fp8_fp8 v[96:99], v[18:19], v[188:189], v[96:99]
	v_exp_f32_e32 v84, v84
	v_exp_f32_e32 v85, v85
	v_exp_f32_e32 v86, v86
	v_exp_f32_e32 v87, v87
	v_pk_fma_f32 v[88:89], v[88:89], s[10:11], v[200:201] op_sel_hi:[1,1,0]
	v_pk_fma_f32 v[90:91], v[90:91], s[10:11], v[200:201] op_sel_hi:[1,1,0]
	v_exp_f32_e32 v88, v88
	v_exp_f32_e32 v89, v89
	v_exp_f32_e32 v90, v90
	v_exp_f32_e32 v91, v91
	v_pk_fma_f32 v[92:93], v[92:93], s[10:11], v[200:201] op_sel_hi:[1,1,0]
	v_pk_fma_f32 v[94:95], v[94:95], s[10:11], v[200:201] op_sel_hi:[1,1,0]
	v_pk_fma_f32 v[96:97], v[96:97], s[10:11], v[200:201] op_sel_hi:[1,1,0]
	v_pk_fma_f32 v[98:99], v[98:99], s[10:11], v[200:201] op_sel_hi:[1,1,0]
	v_exp_f32_e32 v92, v92
	v_exp_f32_e32 v93, v93
	v_exp_f32_e32 v94, v94
	v_exp_f32_e32 v95, v95
	s_nop 0
	v_exp_f32_e32 v96, v96
	v_exp_f32_e32 v97, v97
	v_exp_f32_e32 v98, v98
	v_exp_f32_e32 v99, v99
	v_pk_add_f32 v[248:249], v[84:85], v[86:87]
	v_pk_add_f32 v[82:83], v[88:89], v[90:91]
	v_pk_add_f32 v[172:173], v[92:93], v[94:95]
	v_pk_add_f32 v[202:203], v[96:97], v[98:99]
	v_cvt_pk_fp8_f32 v84, v84, v85
	v_cvt_pk_fp8_f32 v85, v88, v89
	v_pk_add_f32 v[248:249], v[248:249], v[82:83]
	v_pk_add_f32 v[172:173], v[172:173], v[202:203]
	v_cvt_pk_fp8_f32 v84, v86, v87 op_sel:[0,0,1]
	v_cvt_pk_fp8_f32 v85, v90, v91 op_sel:[0,0,1]
	v_pk_add_f32 v[248:249], v[248:249], v[172:173]
	v_cvt_pk_fp8_f32 v86, v92, v93
	v_cvt_pk_fp8_f32 v87, v96, v97
	v_add_f32_e32 v248, v248, v249
	v_cvt_pk_fp8_f32 v86, v94, v95 op_sel:[0,0,1]
	v_cvt_pk_fp8_f32 v87, v98, v99 op_sel:[0,0,1]
	v_cmp_lt_f32_e32 vcc, 0x43800000, v248
	s_cbranch_vccnz .Lbm3_Ag3_redo
	v_add_f32_e32 v197, v197, v248
	s_waitcnt vmcnt(8)
	v_mfma_f32_16x16x32_fp8_fp8 v[148:151], v[36:37], v[84:85], v[148:151]
	v_mfma_f32_16x16x32_fp8_fp8 v[152:155], v[38:39], v[84:85], v[152:155]
	v_mfma_f32_16x16x32_fp8_fp8 v[156:159], v[40:41], v[84:85], v[156:159]
	v_mfma_f32_16x16x32_fp8_fp8 v[160:163], v[42:43], v[84:85], v[160:163]
	v_mfma_f32_16x16x32_fp8_fp8 v[148:151], v[44:45], v[86:87], v[148:151]
	v_mfma_f32_16x16x32_fp8_fp8 v[152:155], v[46:47], v[86:87], v[152:155]
	v_mfma_f32_16x16x32_fp8_fp8 v[156:159], v[48:49], v[86:87], v[156:159]
	v_mfma_f32_16x16x32_fp8_fp8 v[160:163], v[50:51], v[86:87], v[160:163]
	s_branch .Lbm3_Ag3_skip

.Lbm3_blkB:
	s_lshl_b32 s29, s27, 12
	s_add_u32 s30, s40, s29
	s_addc_u32 s31, s41, 0
	global_load_dwordx4 v[2:5], v79, s[30:31]
	global_load_dwordx4 v[6:9], v79, s[30:31] offset:1024
	global_load_dwordx4 v[12:15], v79, s[30:31] offset:2048
	global_load_dwordx4 v[16:19], v79, s[30:31] offset:3072
	s_lshl_b32 s29, s27, 12
	s_add_u32 s30, s62, s29
	s_addc_u32 s31, s63, 0
	global_load_dwordx4 v[36:39], v79, s[30:31]
	global_load_dwordx4 v[40:43], v79, s[30:31] offset:1024
	global_load_dwordx4 v[44:47], v79, s[30:31] offset:2048
	global_load_dwordx4 v[48:51], v79, s[30:31] offset:3072
	s_add_i32 s50, s35, 2
	s_add_i32 s9, s25, -1
	s_min_i32 s50, s50, s9
	s_lshl_b32 s9, s50, 2
	s_add_i32 s9, s9, s46
	v_mov_b32_e32 v76, s9
	ds_read_b32 v76, v76 offset:16384
	s_cmp_ge_i32 s38, s21
	s_cselect_b32 s50, 1, 0
	s_bfe_u32 s29, s48, 0x40000
	s_cmp_eq_u32 s29, 0
	s_cbranch_scc1 .Lbm3_Bg0_skip
	s_waitcnt vmcnt(12)
	v_mfma_f32_16x16x32_fp8_fp8 v[84:87], v[20:21], v[164:165], 0
	v_mfma_f32_16x16x32_fp8_fp8 v[84:87], v[22:23], v[166:167], v[84:87]
	v_mfma_f32_16x16x32_fp8_fp8 v[88:91], v[24:25], v[164:165], 0
	v_mfma_f32_16x16x32_fp8_fp8 v[88:91], v[26:27], v[166:167], v[88:91]
	v_and_b32_e32 v199, s29, v244
	s_cmp_eq_u32 s50, 1
	v_cmp_ne_u32_e32 vcc, 0, v199
	s_cbranch_scc1 .Lbm3_Bg0_near0
	v_add_f32_e32 v200, v81, v190
	v_cndmask_b32_e32 v200, v77, v200, vcc
	s_cmp_eq_u32 s35, 0
	s_cbranch_scc1 .Lbm3_Bg0_first0
	v_mfma_f32_16x16x32_fp8_fp8 v[92:95], v[28:29], v[164:165], 0
	v_mfma_f32_16x16x32_fp8_fp8 v[92:95], v[30:31], v[166:167], v[92:95]
	v_pk_fma_f32 v[84:85], v[84:85], s[10:11], v[200:201] op_sel_hi:[1,1,0]
	v_pk_fma_f32 v[86:87], v[86:87], s[10:11], v[200:201] op_sel_hi:[1,1,0]
	v_mfma_f32_16x16x32_fp8_fp8 v[96:99], v[32:33], v[164:165], 0
	v_mfma_f32_16x16x32_fp8_fp8 v[96:99], v[34:35], v[166:167], v[96:99]
	v_exp_f32_e32 v84, v84
	v_exp_f32_e32 v85, v85
	v_exp_f32_e32 v86, v86
	v_exp_f32_e32 v87, v87
	v_pk_fma_f32 v[88:89], v[88:89], s[10:11], v[200:201] op_sel_hi:[1,1,0]
	v_pk_fma_f32 v[90:91], v[90:91], s[10:11], v[200:201] op_sel_hi:[1,1,0]
	v_exp_f32_e32 v88, v88
	v_exp_f32_e32 v89, v89
	v_exp_f32_e32 v90, v90
	v_exp_f32_e32 v91, v91
	v_pk_fma_f32 v[92:93], v[92:93], s[10:11], v[200:201] op_sel_hi:[1,1,0]
	v_pk_fma_f32 v[94:95], v[94:95], s[10:11], v[200:201] op_sel_hi:[1,1,0]
	v_pk_fma_f32 v[96:97], v[96:97], s[10:11], v[200:201] op_sel_hi:[1,1,0]
	v_pk_fma_f32 v[98:99], v[98:99], s[10:11], v[200:201] op_sel_hi:[1,1,0]
	v_exp_f32_e32 v92, v92
	v_exp_f32_e32 v93, v93
	v_exp_f32_e32 v94, v94
	v_exp_f32_e32 v95, v95
	s_nop 0
	v_exp_f32_e32 v96, v96
	v_exp_f32_e32 v97, v97
	v_exp_f32_e32 v98, v98
	v_exp_f32_e32 v99, v99
	v_pk_add_f32 v[248:249], v[84:85], v[86:87]
	v_pk_add_f32 v[82:83], v[88:89], v[90:91]
	v_pk_add_f32 v[172:173], v[92:93], v[94:95]
	v_pk_add_f32 v[202:203], v[96:97], v[98:99]
	v_cvt_pk_fp8_f32 v84, v84, v85
	v_cvt_pk_fp8_f32 v85, v88, v89
	v_pk_add_f32 v[248:249], v[248:249], v[82:83]
	v_pk_add_f32 v[172:173], v[172:173], v[202:203]
	v_cvt_pk_fp8_f32 v84, v86, v87 op_sel:[0,0,1]
	v_cvt_pk_fp8_f32 v85, v90, v91 op_sel:[0,0,1]
	v_pk_add_f32 v[248:249], v[248:249], v[172:173]
	v_cvt_pk_fp8_f32 v86, v92, v93
	v_cvt_pk_fp8_f32 v87, v96, v97
	v_add_f32_e32 v248, v248, v249
	v_cvt_pk_fp8_f32 v86, v94, v95 op_sel:[0,0,1]
	v_cvt_pk_fp8_f32 v87, v98, v99 op_sel:[0,0,1]
	v_cmp_lt_f32_e32 vcc, 0x43800000, v248
	s_cbranch_vccnz .Lbm3_Bg0_redo
	v_add_f32_e32 v194, v194, v248
	s_waitcnt vmcnt(8)
	v_mfma_f32_16x16x32_fp8_fp8 v[100:103], v[52:53], v[84:85], v[100:103]
	v_mfma_f32_16x16x32_fp8_fp8 v[104:107], v[54:55], v[84:85], v[104:107]
	v_mfma_f32_16x16x32_fp8_fp8 v[108:111], v[56:57], v[84:85], v[108:111]
	v_mfma_f32_16x16x32_fp8_fp8 v[112:115], v[58:59], v[84:85], v[112:115]
	v_mfma_f32_16x16x32_fp8_fp8 v[100:103], v[60:61], v[86:87], v[100:103]
	v_mfma_f32_16x16x32_fp8_fp8 v[104:107], v[62:63], v[86:87], v[104:107]
	v_mfma_f32_16x16x32_fp8_fp8 v[108:111], v[64:65], v[86:87], v[108:111]
	v_mfma_f32_16x16x32_fp8_fp8 v[112:115], v[66:67], v[86:87], v[112:115]
	s_branch .Lbm3_Bg0_skip

.Lbm3_Bg0_skip:
	s_bfe_u32 s29, s48, 0x40004
	s_cmp_eq_u32 s29, 0
	s_cbranch_scc1 .Lbm3_Bg1_skip
	s_waitcnt vmcnt(12)
	v_mfma_f32_16x16x32_fp8_fp8 v[84:87], v[20:21], v[168:169], 0
	v_mfma_f32_16x16x32_fp8_fp8 v[84:87], v[22:23], v[170:171], v[84:87]
	v_mfma_f32_16x16x32_fp8_fp8 v[88:91], v[24:25], v[168:169], 0
	v_mfma_f32_16x16x32_fp8_fp8 v[88:91], v[26:27], v[170:171], v[88:91]
	v_and_b32_e32 v199, s29, v244
	s_cmp_eq_u32 s50, 1
	v_cmp_ne_u32_e32 vcc, 0, v199
	s_cbranch_scc1 .Lbm3_Bg1_near0
	v_add_f32_e32 v200, v81, v191
	v_cndmask_b32_e32 v200, v77, v200, vcc
	s_cmp_eq_u32 s35, 0
	s_cbranch_scc1 .Lbm3_Bg1_first0
	v_mfma_f32_16x16x32_fp8_fp8 v[92:95], v[28:29], v[168:169], 0
	v_mfma_f32_16x16x32_fp8_fp8 v[92:95], v[30:31], v[170:171], v[92:95]
	v_pk_fma_f32 v[84:85], v[84:85], s[10:11], v[200:201] op_sel_hi:[1,1,0]
	v_pk_fma_f32 v[86:87], v[86:87], s[10:11], v[200:201] op_sel_hi:[1,1,0]
	v_mfma_f32_16x16x32_fp8_fp8 v[96:99], v[32:33], v[168:169], 0
	v_mfma_f32_16x16x32_fp8_fp8 v[96:99], v[34:35], v[170:171], v[96:99]
	v_exp_f32_e32 v84, v84
	v_exp_f32_e32 v85, v85
	v_exp_f32_e32 v86, v86
	v_exp_f32_e32 v87, v87
	v_pk_fma_f32 v[88:89], v[88:89], s[10:11], v[200:201] op_sel_hi:[1,1,0]
	v_pk_fma_f32 v[90:91], v[90:91], s[10:11], v[200:201] op_sel_hi:[1,1,0]
	v_exp_f32_e32 v88, v88
	v_exp_f32_e32 v89, v89
	v_exp_f32_e32 v90, v90
	v_exp_f32_e32 v91, v91
	v_pk_fma_f32 v[92:93], v[92:93], s[10:11], v[200:201] op_sel_hi:[1,1,0]
	v_pk_fma_f32 v[94:95], v[94:95], s[10:11], v[200:201] op_sel_hi:[1,1,0]
	v_pk_fma_f32 v[96:97], v[96:97], s[10:11], v[200:201] op_sel_hi:[1,1,0]
	v_pk_fma_f32 v[98:99], v[98:99], s[10:11], v[200:201] op_sel_hi:[1,1,0]
	v_exp_f32_e32 v92, v92
	v_exp_f32_e32 v93, v93
	v_exp_f32_e32 v94, v94
	v_exp_f32_e32 v95, v95
	s_nop 0
	v_exp_f32_e32 v96, v96
	v_exp_f32_e32 v97, v97
	v_exp_f32_e32 v98, v98
	v_exp_f32_e32 v99, v99
	v_pk_add_f32 v[248:249], v[84:85], v[86:87]
	v_pk_add_f32 v[82:83], v[88:89], v[90:91]
	v_pk_add_f32 v[172:173], v[92:93], v[94:95]
	v_pk_add_f32 v[202:203], v[96:97], v[98:99]
	v_cvt_pk_fp8_f32 v84, v84, v85
	v_cvt_pk_fp8_f32 v85, v88, v89
	v_pk_add_f32 v[248:249], v[248:249], v[82:83]
	v_pk_add_f32 v[172:173], v[172:173], v[202:203]
	v_cvt_pk_fp8_f32 v84, v86, v87 op_sel:[0,0,1]
	v_cvt_pk_fp8_f32 v85, v90, v91 op_sel:[0,0,1]
	v_pk_add_f32 v[248:249], v[248:249], v[172:173]
	v_cvt_pk_fp8_f32 v86, v92, v93
	v_cvt_pk_fp8_f32 v87, v96, v97
	v_add_f32_e32 v248, v248, v249
	v_cvt_pk_fp8_f32 v86, v94, v95 op_sel:[0,0,1]
	v_cvt_pk_fp8_f32 v87, v98, v99 op_sel:[0,0,1]
	v_cmp_lt_f32_e32 vcc, 0x43800000, v248
	s_cbranch_vccnz .Lbm3_Bg1_redo
	v_add_f32_e32 v195, v195, v248
	s_waitcnt vmcnt(8)
	v_mfma_f32_16x16x32_fp8_fp8 v[116:119], v[52:53], v[84:85], v[116:119]
	v_mfma_f32_16x16x32_fp8_fp8 v[120:123], v[54:55], v[84:85], v[120:123]
	v_mfma_f32_16x16x32_fp8_fp8 v[124:127], v[56:57], v[84:85], v[124:127]
	v_mfma_f32_16x16x32_fp8_fp8 v[128:131], v[58:59], v[84:85], v[128:131]
	v_mfma_f32_16x16x32_fp8_fp8 v[116:119], v[60:61], v[86:87], v[116:119]
	v_mfma_f32_16x16x32_fp8_fp8 v[120:123], v[62:63], v[86:87], v[120:123]
	v_mfma_f32_16x16x32_fp8_fp8 v[124:127], v[64:65], v[86:87], v[124:127]
	v_mfma_f32_16x16x32_fp8_fp8 v[128:131], v[66:67], v[86:87], v[128:131]
	s_branch .Lbm3_Bg1_skip

.Lbm3_Bg1_skip:
	s_bfe_u32 s29, s48, 0x40008
	s_cmp_eq_u32 s29, 0
	s_cbranch_scc1 .Lbm3_Bg2_skip
	s_waitcnt vmcnt(12)
	v_mfma_f32_16x16x32_fp8_fp8 v[84:87], v[20:21], v[182:183], 0
	v_mfma_f32_16x16x32_fp8_fp8 v[84:87], v[22:23], v[184:185], v[84:87]
	v_mfma_f32_16x16x32_fp8_fp8 v[88:91], v[24:25], v[182:183], 0
	v_mfma_f32_16x16x32_fp8_fp8 v[88:91], v[26:27], v[184:185], v[88:91]
	v_and_b32_e32 v199, s29, v244
	s_cmp_eq_u32 s50, 1
	v_cmp_ne_u32_e32 vcc, 0, v199
	s_cbranch_scc1 .Lbm3_Bg2_near0
	v_add_f32_e32 v200, v81, v192
	v_cndmask_b32_e32 v200, v77, v200, vcc
	s_cmp_eq_u32 s35, 0
	s_cbranch_scc1 .Lbm3_Bg2_first0
	v_mfma_f32_16x16x32_fp8_fp8 v[92:95], v[28:29], v[182:183], 0
	v_mfma_f32_16x16x32_fp8_fp8 v[92:95], v[30:31], v[184:185], v[92:95]
	v_pk_fma_f32 v[84:85], v[84:85], s[10:11], v[200:201] op_sel_hi:[1,1,0]
	v_pk_fma_f32 v[86:87], v[86:87], s[10:11], v[200:201] op_sel_hi:[1,1,0]
	v_mfma_f32_16x16x32_fp8_fp8 v[96:99], v[32:33], v[182:183], 0
	v_mfma_f32_16x16x32_fp8_fp8 v[96:99], v[34:35], v[184:185], v[96:99]
	v_exp_f32_e32 v84, v84
	v_exp_f32_e32 v85, v85
	v_exp_f32_e32 v86, v86
	v_exp_f32_e32 v87, v87
	v_pk_fma_f32 v[88:89], v[88:89], s[10:11], v[200:201] op_sel_hi:[1,1,0]
	v_pk_fma_f32 v[90:91], v[90:91], s[10:11], v[200:201] op_sel_hi:[1,1,0]
	v_exp_f32_e32 v88, v88
	v_exp_f32_e32 v89, v89
	v_exp_f32_e32 v90, v90
	v_exp_f32_e32 v91, v91
	v_pk_fma_f32 v[92:93], v[92:93], s[10:11], v[200:201] op_sel_hi:[1,1,0]
	v_pk_fma_f32 v[94:95], v[94:95], s[10:11], v[200:201] op_sel_hi:[1,1,0]
	v_pk_fma_f32 v[96:97], v[96:97], s[10:11], v[200:201] op_sel_hi:[1,1,0]
	v_pk_fma_f32 v[98:99], v[98:99], s[10:11], v[200:201] op_sel_hi:[1,1,0]
	v_exp_f32_e32 v92, v92
	v_exp_f32_e32 v93, v93
	v_exp_f32_e32 v94, v94
	v_exp_f32_e32 v95, v95
	s_nop 0
	v_exp_f32_e32 v96, v96
	v_exp_f32_e32 v97, v97
	v_exp_f32_e32 v98, v98
	v_exp_f32_e32 v99, v99
	v_pk_add_f32 v[248:249], v[84:85], v[86:87]
	v_pk_add_f32 v[82:83], v[88:89], v[90:91]
	v_pk_add_f32 v[172:173], v[92:93], v[94:95]
	v_pk_add_f32 v[202:203], v[96:97], v[98:99]
	v_cvt_pk_fp8_f32 v84, v84, v85
	v_cvt_pk_fp8_f32 v85, v88, v89
	v_pk_add_f32 v[248:249], v[248:249], v[82:83]
	v_pk_add_f32 v[172:173], v[172:173], v[202:203]
	v_cvt_pk_fp8_f32 v84, v86, v87 op_sel:[0,0,1]
	v_cvt_pk_fp8_f32 v85, v90, v91 op_sel:[0,0,1]
	v_pk_add_f32 v[248:249], v[248:249], v[172:173]
	v_cvt_pk_fp8_f32 v86, v92, v93
	v_cvt_pk_fp8_f32 v87, v96, v97
	v_add_f32_e32 v248, v248, v249
	v_cvt_pk_fp8_f32 v86, v94, v95 op_sel:[0,0,1]
	v_cvt_pk_fp8_f32 v87, v98, v99 op_sel:[0,0,1]
	v_cmp_lt_f32_e32 vcc, 0x43800000, v248
	s_cbranch_vccnz .Lbm3_Bg2_redo
	v_add_f32_e32 v196, v196, v248
	s_waitcnt vmcnt(8)
	v_mfma_f32_16x16x32_fp8_fp8 v[132:135], v[52:53], v[84:85], v[132:135]
	v_mfma_f32_16x16x32_fp8_fp8 v[136:139], v[54:55], v[84:85], v[136:139]
	v_mfma_f32_16x16x32_fp8_fp8 v[140:143], v[56:57], v[84:85], v[140:143]
	v_mfma_f32_16x16x32_fp8_fp8 v[144:147], v[58:59], v[84:85], v[144:147]
	v_mfma_f32_16x16x32_fp8_fp8 v[132:135], v[60:61], v[86:87], v[132:135]
	v_mfma_f32_16x16x32_fp8_fp8 v[136:139], v[62:63], v[86:87], v[136:139]
	v_mfma_f32_16x16x32_fp8_fp8 v[140:143], v[64:65], v[86:87], v[140:143]
	v_mfma_f32_16x16x32_fp8_fp8 v[144:147], v[66:67], v[86:87], v[144:147]
	s_branch .Lbm3_Bg2_skip

.Lbm3_Bg2_skip:
	s_bfe_u32 s29, s48, 0x4000c
	s_cmp_eq_u32 s29, 0
	s_cbranch_scc1 .Lbm3_Bg3_skip
	s_waitcnt vmcnt(12)
	v_mfma_f32_16x16x32_fp8_fp8 v[84:87], v[20:21], v[186:187], 0
	v_mfma_f32_16x16x32_fp8_fp8 v[84:87], v[22:23], v[188:189], v[84:87]
	v_mfma_f32_16x16x32_fp8_fp8 v[88:91], v[24:25], v[186:187], 0
	v_mfma_f32_16x16x32_fp8_fp8 v[88:91], v[26:27], v[188:189], v[88:91]
	v_and_b32_e32 v199, s29, v244
	s_cmp_eq_u32 s50, 1
	v_cmp_ne_u32_e32 vcc, 0, v199
	s_cbranch_scc1 .Lbm3_Bg3_near0
	v_add_f32_e32 v200, v81, v193
	v_cndmask_b32_e32 v200, v77, v200, vcc
	s_cmp_eq_u32 s35, 0
	s_cbranch_scc1 .Lbm3_Bg3_first0
	v_mfma_f32_16x16x32_fp8_fp8 v[92:95], v[28:29], v[186:187], 0
	v_mfma_f32_16x16x32_fp8_fp8 v[92:95], v[30:31], v[188:189], v[92:95]
	v_pk_fma_f32 v[84:85], v[84:85], s[10:11], v[200:201] op_sel_hi:[1,1,0]
	v_pk_fma_f32 v[86:87], v[86:87], s[10:11], v[200:201] op_sel_hi:[1,1,0]
	v_mfma_f32_16x16x32_fp8_fp8 v[96:99], v[32:33], v[186:187], 0
	v_mfma_f32_16x16x32_fp8_fp8 v[96:99], v[34:35], v[188:189], v[96:99]
	v_exp_f32_e32 v84, v84
	v_exp_f32_e32 v85, v85
	v_exp_f32_e32 v86, v86
	v_exp_f32_e32 v87, v87
	v_pk_fma_f32 v[88:89], v[88:89], s[10:11], v[200:201] op_sel_hi:[1,1,0]
	v_pk_fma_f32 v[90:91], v[90:91], s[10:11], v[200:201] op_sel_hi:[1,1,0]
	v_exp_f32_e32 v88, v88
	v_exp_f32_e32 v89, v89
	v_exp_f32_e32 v90, v90
	v_exp_f32_e32 v91, v91
	v_pk_fma_f32 v[92:93], v[92:93], s[10:11], v[200:201] op_sel_hi:[1,1,0]
	v_pk_fma_f32 v[94:95], v[94:95], s[10:11], v[200:201] op_sel_hi:[1,1,0]
	v_pk_fma_f32 v[96:97], v[96:97], s[10:11], v[200:201] op_sel_hi:[1,1,0]
	v_pk_fma_f32 v[98:99], v[98:99], s[10:11], v[200:201] op_sel_hi:[1,1,0]
	v_exp_f32_e32 v92, v92
	v_exp_f32_e32 v93, v93
	v_exp_f32_e32 v94, v94
	v_exp_f32_e32 v95, v95
	s_nop 0
	v_exp_f32_e32 v96, v96
	v_exp_f32_e32 v97, v97
	v_exp_f32_e32 v98, v98
	v_exp_f32_e32 v99, v99
	v_pk_add_f32 v[248:249], v[84:85], v[86:87]
	v_pk_add_f32 v[82:83], v[88:89], v[90:91]
	v_pk_add_f32 v[172:173], v[92:93], v[94:95]
	v_pk_add_f32 v[202:203], v[96:97], v[98:99]
	v_cvt_pk_fp8_f32 v84, v84, v85
	v_cvt_pk_fp8_f32 v85, v88, v89
	v_pk_add_f32 v[248:249], v[248:249], v[82:83]
	v_pk_add_f32 v[172:173], v[172:173], v[202:203]
	v_cvt_pk_fp8_f32 v84, v86, v87 op_sel:[0,0,1]
	v_cvt_pk_fp8_f32 v85, v90, v91 op_sel:[0,0,1]
	v_pk_add_f32 v[248:249], v[248:249], v[172:173]
	v_cvt_pk_fp8_f32 v86, v92, v93
	v_cvt_pk_fp8_f32 v87, v96, v97
	v_add_f32_e32 v248, v248, v249
	v_cvt_pk_fp8_f32 v86, v94, v95 op_sel:[0,0,1]
	v_cvt_pk_fp8_f32 v87, v98, v99 op_sel:[0,0,1]
	v_cmp_lt_f32_e32 vcc, 0x43800000, v248
	s_cbranch_vccnz .Lbm3_Bg3_redo
	v_add_f32_e32 v197, v197, v248
	s_waitcnt vmcnt(8)
	v_mfma_f32_16x16x32_fp8_fp8 v[148:151], v[52:53], v[84:85], v[148:151]
	v_mfma_f32_16x16x32_fp8_fp8 v[152:155], v[54:55], v[84:85], v[152:155]
	v_mfma_f32_16x16x32_fp8_fp8 v[156:159], v[56:57], v[84:85], v[156:159]
	v_mfma_f32_16x16x32_fp8_fp8 v[160:163], v[58:59], v[84:85], v[160:163]
	v_mfma_f32_16x16x32_fp8_fp8 v[148:151], v[60:61], v[86:87], v[148:151]
	v_mfma_f32_16x16x32_fp8_fp8 v[152:155], v[62:63], v[86:87], v[152:155]
	v_mfma_f32_16x16x32_fp8_fp8 v[156:159], v[64:65], v[86:87], v[156:159]
	v_mfma_f32_16x16x32_fp8_fp8 v[160:163], v[66:67], v[86:87], v[160:163]
	s_branch .Lbm3_Bg3_skip
